# v19 + GEMM loops: the load phase of each half runs at s_setprio 2 (above the partner's MFMA cluster at 1) instead of 0
# speedup vs baseline: 1.0123x; 1.0056x over previous
.LBB0_239:
	s_add_u32 s10, s12, 0xfff80080
	s_addc_u32 s11, s13, -1
	s_add_i32 s64, 0, 0x10000
	s_cmp_eq_u32 s70, 28
	s_cselect_b32 s39, s25, s11
	s_cselect_b32 s38, s43, s10
	s_cselect_b32 s15, s23, s69
	s_cselect_b32 s14, s67, s68
	s_add_i32 s65, 0, 0x14000
	v_add_u32_e32 v152, s64, v160
	v_add_u32_e32 v156, s65, v160
	ds_read_b128 v[140:143], v152
	ds_read_b128 v[144:147], v152 offset:1024
	ds_read_b128 v[148:151], v152 offset:2048
	ds_read_b128 v[152:155], v152 offset:3072
	ds_read_b128 v[162:165], v156
	ds_read_b128 v[166:169], v156 offset:1024
	ds_read_b128 v[170:173], v156 offset:2048
	ds_read_b128 v[180:183], v156 offset:3072
	v_lshl_add_u64 v[156:157], s[12:13], 0, v[138:139]
	s_add_i32 m0, s40, 0xc000
	ds_read_b128 v[184:187], v161
	ds_read_b128 v[188:191], v161 offset:1024
	ds_read_b128 v[192:195], v161 offset:2048
	ds_read_b128 v[196:199], v161 offset:3072
	ds_read_b128 v[200:203], v161 offset:4096
	ds_read_b128 v[204:207], v161 offset:5120
	ds_read_b128 v[208:211], v161 offset:6144
	ds_read_b128 v[212:215], v161 offset:7168
	global_load_lds_dwordx4 v[156:157], off
	v_lshl_add_u64 v[156:157], s[12:13], 0, v[136:137]
	s_add_i32 m0, s40, 0xe000
	s_nop 0
	global_load_lds_dwordx4 v[156:157], off
	s_waitcnt vmcnt(8)
	s_waitcnt lgkmcnt(0)
	s_barrier
	s_setprio 1
	s_waitcnt lgkmcnt(0)
	v_mfma_f32_16x16x32_bf16 v[126:129], v[140:143], v[184:187], v[126:129]
	v_mfma_f32_16x16x32_bf16 v[122:125], v[148:151], v[184:187], v[122:125]
	v_mfma_f32_16x16x32_bf16 v[110:113], v[140:143], v[192:195], v[110:113]
	v_mfma_f32_16x16x32_bf16 v[106:109], v[148:151], v[192:195], v[106:109]
	v_mfma_f32_16x16x32_bf16 v[94:97], v[140:143], v[200:203], v[94:97]
	v_mfma_f32_16x16x32_bf16 v[90:93], v[148:151], v[200:203], v[90:93]
	v_mfma_f32_16x16x32_bf16 v[78:81], v[140:143], v[208:211], v[78:81]
	v_mfma_f32_16x16x32_bf16 v[74:77], v[148:151], v[208:211], v[74:77]
	v_mfma_f32_16x16x32_bf16 v[126:129], v[144:147], v[188:191], v[126:129]
	v_mfma_f32_16x16x32_bf16 v[122:125], v[152:155], v[188:191], v[122:125]
	v_mfma_f32_16x16x32_bf16 v[110:113], v[144:147], v[196:199], v[110:113]
	v_mfma_f32_16x16x32_bf16 v[106:109], v[152:155], v[196:199], v[106:109]
	v_mfma_f32_16x16x32_bf16 v[94:97], v[144:147], v[204:207], v[94:97]
	v_mfma_f32_16x16x32_bf16 v[90:93], v[152:155], v[204:207], v[90:93]
	v_mfma_f32_16x16x32_bf16 v[78:81], v[144:147], v[212:215], v[78:81]
	v_mfma_f32_16x16x32_bf16 v[74:77], v[152:155], v[212:215], v[74:77]
	s_setprio 0
	s_setprio 1
	v_mfma_f32_16x16x32_bf16 v[118:121], v[162:165], v[184:187], v[118:121]
	v_mfma_f32_16x16x32_bf16 v[114:117], v[170:173], v[184:187], v[114:117]
	v_mfma_f32_16x16x32_bf16 v[102:105], v[162:165], v[192:195], v[102:105]
	v_mfma_f32_16x16x32_bf16 v[98:101], v[170:173], v[192:195], v[98:101]
	v_mfma_f32_16x16x32_bf16 v[86:89], v[162:165], v[200:203], v[86:89]
	v_mfma_f32_16x16x32_bf16 v[82:85], v[170:173], v[200:203], v[82:85]
	v_mfma_f32_16x16x32_bf16 v[70:73], v[162:165], v[208:211], v[70:73]
	v_mfma_f32_16x16x32_bf16 v[66:69], v[170:173], v[208:211], v[66:69]
	v_mfma_f32_16x16x32_bf16 v[118:121], v[166:169], v[188:191], v[118:121]
	v_mfma_f32_16x16x32_bf16 v[114:117], v[180:183], v[188:191], v[114:117]
	v_mfma_f32_16x16x32_bf16 v[102:105], v[166:169], v[196:199], v[102:105]
	v_mfma_f32_16x16x32_bf16 v[98:101], v[180:183], v[196:199], v[98:101]
	v_mfma_f32_16x16x32_bf16 v[86:89], v[166:169], v[204:207], v[86:89]
	v_mfma_f32_16x16x32_bf16 v[82:85], v[180:183], v[204:207], v[82:85]
	v_mfma_f32_16x16x32_bf16 v[70:73], v[166:169], v[212:215], v[70:73]
	v_mfma_f32_16x16x32_bf16 v[66:69], v[180:183], v[212:215], v[66:69]
	s_setprio 2
	s_barrier
	s_add_i32 s10, s64, s37
	v_lshl_add_u64 v[156:157], s[14:15], 0, v[0:1]
	s_mov_b32 m0, s10
	ds_read_b128 v[184:187], v161 offset:16384
	ds_read_b128 v[188:191], v161 offset:17408
	ds_read_b128 v[192:195], v161 offset:18432
	ds_read_b128 v[196:199], v161 offset:19456
	ds_read_b128 v[200:203], v161 offset:20480
	ds_read_b128 v[204:207], v161 offset:21504
	ds_read_b128 v[208:211], v161 offset:22528
	ds_read_b128 v[212:215], v161 offset:23552
	global_load_lds_dwordx4 v[156:157], off
	s_add_i32 m0, s10, 0x2000
	s_add_u32 s10, s14, 0x80000
	v_lshl_add_u64 v[174:175], s[14:15], 0, v[130:131]
	s_addc_u32 s11, s15, 0
	s_add_i32 s64, s65, s37
	global_load_lds_dwordx4 v[174:175], off
	v_lshl_add_u64 v[176:177], s[10:11], 0, v[0:1]
	s_mov_b32 m0, s64
	v_lshl_add_u64 v[178:179], s[38:39], 0, v[132:133]
	global_load_lds_dwordx4 v[176:177], off
	v_lshl_add_u64 v[176:177], s[10:11], 0, v[130:131]
	s_add_i32 m0, s64, 0x2000
	s_nop 0
	global_load_lds_dwordx4 v[176:177], off
	v_lshl_add_u64 v[176:177], s[38:39], 0, v[134:135]
	s_mov_b32 m0, s40
	s_nop 0
	global_load_lds_dwordx4 v[176:177], off
	s_mov_b32 m0, s41
	s_nop 0
	global_load_lds_dwordx4 v[178:179], off
	s_waitcnt vmcnt(8)
	s_waitcnt lgkmcnt(0)
	s_barrier
	s_setprio 1
	s_waitcnt lgkmcnt(0)
	v_mfma_f32_16x16x32_bf16 v[62:65], v[140:143], v[184:187], v[62:65]
	v_mfma_f32_16x16x32_bf16 v[58:61], v[148:151], v[184:187], v[58:61]
	v_mfma_f32_16x16x32_bf16 v[46:49], v[140:143], v[192:195], v[46:49]
	v_mfma_f32_16x16x32_bf16 v[42:45], v[148:151], v[192:195], v[42:45]
	v_mfma_f32_16x16x32_bf16 v[30:33], v[140:143], v[200:203], v[30:33]
	v_mfma_f32_16x16x32_bf16 v[26:29], v[148:151], v[200:203], v[26:29]
	v_mfma_f32_16x16x32_bf16 v[14:17], v[140:143], v[208:211], v[14:17]
	v_mfma_f32_16x16x32_bf16 v[10:13], v[148:151], v[208:211], v[10:13]
	v_mfma_f32_16x16x32_bf16 v[62:65], v[144:147], v[188:191], v[62:65]
	v_mfma_f32_16x16x32_bf16 v[58:61], v[152:155], v[188:191], v[58:61]
	v_mfma_f32_16x16x32_bf16 v[46:49], v[144:147], v[196:199], v[46:49]
	v_mfma_f32_16x16x32_bf16 v[42:45], v[152:155], v[196:199], v[42:45]
	v_mfma_f32_16x16x32_bf16 v[30:33], v[144:147], v[204:207], v[30:33]
	v_mfma_f32_16x16x32_bf16 v[26:29], v[152:155], v[204:207], v[26:29]
	v_mfma_f32_16x16x32_bf16 v[14:17], v[144:147], v[212:215], v[14:17]
	v_mfma_f32_16x16x32_bf16 v[10:13], v[152:155], v[212:215], v[10:13]
	s_setprio 0
	s_setprio 1
	v_mfma_f32_16x16x32_bf16 v[54:57], v[162:165], v[184:187], v[54:57]
	v_mfma_f32_16x16x32_bf16 v[50:53], v[170:173], v[184:187], v[50:53]
	v_mfma_f32_16x16x32_bf16 v[38:41], v[162:165], v[192:195], v[38:41]
	v_mfma_f32_16x16x32_bf16 v[34:37], v[170:173], v[192:195], v[34:37]
	v_mfma_f32_16x16x32_bf16 v[22:25], v[162:165], v[200:203], v[22:25]
	v_mfma_f32_16x16x32_bf16 v[18:21], v[170:173], v[200:203], v[18:21]
	v_mfma_f32_16x16x32_bf16 v[6:9], v[162:165], v[208:211], v[6:9]
	v_mfma_f32_16x16x32_bf16 v[2:5], v[170:173], v[208:211], v[2:5]
	v_mfma_f32_16x16x32_bf16 v[54:57], v[166:169], v[188:191], v[54:57]
	v_mfma_f32_16x16x32_bf16 v[50:53], v[180:183], v[188:191], v[50:53]
	v_mfma_f32_16x16x32_bf16 v[38:41], v[166:169], v[196:199], v[38:41]
	v_mfma_f32_16x16x32_bf16 v[34:37], v[180:183], v[196:199], v[34:37]
	v_mfma_f32_16x16x32_bf16 v[22:25], v[166:169], v[204:207], v[22:25]
	v_mfma_f32_16x16x32_bf16 v[18:21], v[180:183], v[204:207], v[18:21]
	v_mfma_f32_16x16x32_bf16 v[6:9], v[166:169], v[212:215], v[6:9]
	v_mfma_f32_16x16x32_bf16 v[2:5], v[180:183], v[212:215], v[2:5]
	s_setprio 2
	s_barrier
	s_add_i32 s64, 0, 0x18000
	s_add_i32 s65, 0, 0x1c000
	v_add_u32_e32 v152, s64, v160
	v_add_u32_e32 v180, s65, v160
	ds_read_b128 v[140:143], v152
	ds_read_b128 v[144:147], v152 offset:1024
	ds_read_b128 v[148:151], v152 offset:2048
	ds_read_b128 v[152:155], v152 offset:3072
	ds_read_b128 v[162:165], v180
	ds_read_b128 v[166:169], v180 offset:1024
	ds_read_b128 v[170:173], v180 offset:2048
	ds_read_b128 v[180:183], v180 offset:3072
	s_add_u32 s10, s38, 0x80000
	s_addc_u32 s11, s39, 0
	s_mov_b32 m0, s44
	v_lshl_add_u64 v[216:217], s[10:11], 0, v[134:135]
	ds_read_b128 v[184:187], v161 offset:32768
	ds_read_b128 v[188:191], v161 offset:33792
	ds_read_b128 v[192:195], v161 offset:34816
	ds_read_b128 v[196:199], v161 offset:35840
	ds_read_b128 v[200:203], v161 offset:36864
	ds_read_b128 v[204:207], v161 offset:37888
	ds_read_b128 v[208:211], v161 offset:38912
	ds_read_b128 v[212:215], v161 offset:39936
	global_load_lds_dwordx4 v[216:217], off
	v_lshl_add_u64 v[216:217], s[10:11], 0, v[132:133]
	s_mov_b32 m0, s45
	s_nop 0
	global_load_lds_dwordx4 v[216:217], off
	s_waitcnt vmcnt(8)
	s_waitcnt lgkmcnt(0)
	s_barrier
	s_setprio 1
	s_waitcnt lgkmcnt(0)
	v_mfma_f32_16x16x32_bf16 v[126:129], v[140:143], v[184:187], v[126:129]
	v_mfma_f32_16x16x32_bf16 v[122:125], v[148:151], v[184:187], v[122:125]
	v_mfma_f32_16x16x32_bf16 v[110:113], v[140:143], v[192:195], v[110:113]
	v_mfma_f32_16x16x32_bf16 v[106:109], v[148:151], v[192:195], v[106:109]
	v_mfma_f32_16x16x32_bf16 v[94:97], v[140:143], v[200:203], v[94:97]
	v_mfma_f32_16x16x32_bf16 v[90:93], v[148:151], v[200:203], v[90:93]
	v_mfma_f32_16x16x32_bf16 v[78:81], v[140:143], v[208:211], v[78:81]
	v_mfma_f32_16x16x32_bf16 v[74:77], v[148:151], v[208:211], v[74:77]
	v_mfma_f32_16x16x32_bf16 v[126:129], v[144:147], v[188:191], v[126:129]
	v_mfma_f32_16x16x32_bf16 v[122:125], v[152:155], v[188:191], v[122:125]
	v_mfma_f32_16x16x32_bf16 v[110:113], v[144:147], v[196:199], v[110:113]
	v_mfma_f32_16x16x32_bf16 v[106:109], v[152:155], v[196:199], v[106:109]
	v_mfma_f32_16x16x32_bf16 v[94:97], v[144:147], v[204:207], v[94:97]
	v_mfma_f32_16x16x32_bf16 v[90:93], v[152:155], v[204:207], v[90:93]
	v_mfma_f32_16x16x32_bf16 v[78:81], v[144:147], v[212:215], v[78:81]
	v_mfma_f32_16x16x32_bf16 v[74:77], v[152:155], v[212:215], v[74:77]
	s_setprio 0
	s_setprio 1
	v_mfma_f32_16x16x32_bf16 v[118:121], v[162:165], v[184:187], v[118:121]
	v_mfma_f32_16x16x32_bf16 v[114:117], v[170:173], v[184:187], v[114:117]
	v_mfma_f32_16x16x32_bf16 v[102:105], v[162:165], v[192:195], v[102:105]
	v_mfma_f32_16x16x32_bf16 v[98:101], v[170:173], v[192:195], v[98:101]
	v_mfma_f32_16x16x32_bf16 v[86:89], v[162:165], v[200:203], v[86:89]
	v_mfma_f32_16x16x32_bf16 v[82:85], v[170:173], v[200:203], v[82:85]
	v_mfma_f32_16x16x32_bf16 v[70:73], v[162:165], v[208:211], v[70:73]
	v_mfma_f32_16x16x32_bf16 v[66:69], v[170:173], v[208:211], v[66:69]
	v_mfma_f32_16x16x32_bf16 v[118:121], v[166:169], v[188:191], v[118:121]
	v_mfma_f32_16x16x32_bf16 v[114:117], v[180:183], v[188:191], v[114:117]
	v_mfma_f32_16x16x32_bf16 v[102:105], v[166:169], v[196:199], v[102:105]
	v_mfma_f32_16x16x32_bf16 v[98:101], v[180:183], v[196:199], v[98:101]
	v_mfma_f32_16x16x32_bf16 v[86:89], v[166:169], v[204:207], v[86:89]
	v_mfma_f32_16x16x32_bf16 v[82:85], v[180:183], v[204:207], v[82:85]
	v_mfma_f32_16x16x32_bf16 v[70:73], v[166:169], v[212:215], v[70:73]
	v_mfma_f32_16x16x32_bf16 v[66:69], v[180:183], v[212:215], v[66:69]
	s_setprio 2
	s_barrier
	s_add_i32 s10, s64, s37
	v_lshl_add_u64 v[156:157], v[156:157], 0, s[94:95]
	s_mov_b32 m0, s10
	ds_read_b128 v[184:187], v161 offset:49152
	ds_read_b128 v[188:191], v161 offset:50176
	ds_read_b128 v[192:195], v161 offset:51200
	ds_read_b128 v[196:199], v161 offset:52224
	ds_read_b128 v[200:203], v161 offset:53248
	ds_read_b128 v[204:207], v161 offset:54272
	ds_read_b128 v[208:211], v161 offset:55296
	ds_read_b128 v[212:215], v161 offset:56320
	global_load_lds_dwordx4 v[156:157], off
	s_add_i32 m0, s10, 0x2000
	s_add_u32 s10, s14, 0x80080
	v_lshl_add_u64 v[156:157], v[174:175], 0, s[94:95]
	s_addc_u32 s11, s15, 0
	s_add_i32 s14, s65, s37
	global_load_lds_dwordx4 v[156:157], off
	v_lshl_add_u64 v[156:157], s[10:11], 0, v[0:1]
	s_mov_b32 m0, s14
	s_nop 0
	global_load_lds_dwordx4 v[156:157], off
	v_lshl_add_u64 v[156:157], s[10:11], 0, v[130:131]
	s_add_i32 m0, s14, 0x2000
	s_nop 0
	global_load_lds_dwordx4 v[156:157], off
	v_lshl_add_u64 v[156:157], v[176:177], 0, s[94:95]
	s_mov_b32 m0, s60
	s_nop 0
	global_load_lds_dwordx4 v[156:157], off
	v_lshl_add_u64 v[156:157], v[178:179], 0, s[94:95]
	s_mov_b32 m0, s61
	s_nop 0
	global_load_lds_dwordx4 v[156:157], off
	s_waitcnt vmcnt(8)
	s_waitcnt lgkmcnt(0)
	s_barrier
	s_setprio 1
	s_waitcnt lgkmcnt(0)
	v_mfma_f32_16x16x32_bf16 v[62:65], v[140:143], v[184:187], v[62:65]
	v_mfma_f32_16x16x32_bf16 v[58:61], v[148:151], v[184:187], v[58:61]
	v_mfma_f32_16x16x32_bf16 v[46:49], v[140:143], v[192:195], v[46:49]
	v_mfma_f32_16x16x32_bf16 v[42:45], v[148:151], v[192:195], v[42:45]
	v_mfma_f32_16x16x32_bf16 v[30:33], v[140:143], v[200:203], v[30:33]
	v_mfma_f32_16x16x32_bf16 v[26:29], v[148:151], v[200:203], v[26:29]
	v_mfma_f32_16x16x32_bf16 v[14:17], v[140:143], v[208:211], v[14:17]
	v_mfma_f32_16x16x32_bf16 v[10:13], v[148:151], v[208:211], v[10:13]
	v_mfma_f32_16x16x32_bf16 v[62:65], v[144:147], v[188:191], v[62:65]
	v_mfma_f32_16x16x32_bf16 v[58:61], v[152:155], v[188:191], v[58:61]
	v_mfma_f32_16x16x32_bf16 v[46:49], v[144:147], v[196:199], v[46:49]
	v_mfma_f32_16x16x32_bf16 v[42:45], v[152:155], v[196:199], v[42:45]
	v_mfma_f32_16x16x32_bf16 v[30:33], v[144:147], v[204:207], v[30:33]
	v_mfma_f32_16x16x32_bf16 v[26:29], v[152:155], v[204:207], v[26:29]
	v_mfma_f32_16x16x32_bf16 v[14:17], v[144:147], v[212:215], v[14:17]
	v_mfma_f32_16x16x32_bf16 v[10:13], v[152:155], v[212:215], v[10:13]
	s_setprio 0
	s_setprio 1
	v_mfma_f32_16x16x32_bf16 v[54:57], v[162:165], v[184:187], v[54:57]
	v_mfma_f32_16x16x32_bf16 v[50:53], v[170:173], v[184:187], v[50:53]
	v_mfma_f32_16x16x32_bf16 v[38:41], v[162:165], v[192:195], v[38:41]
	v_mfma_f32_16x16x32_bf16 v[34:37], v[170:173], v[192:195], v[34:37]
	v_mfma_f32_16x16x32_bf16 v[22:25], v[162:165], v[200:203], v[22:25]
	v_mfma_f32_16x16x32_bf16 v[18:21], v[170:173], v[200:203], v[18:21]
	v_mfma_f32_16x16x32_bf16 v[6:9], v[162:165], v[208:211], v[6:9]
	v_mfma_f32_16x16x32_bf16 v[2:5], v[170:173], v[208:211], v[2:5]
	v_mfma_f32_16x16x32_bf16 v[54:57], v[166:169], v[188:191], v[54:57]
	v_mfma_f32_16x16x32_bf16 v[50:53], v[180:183], v[188:191], v[50:53]
	v_mfma_f32_16x16x32_bf16 v[38:41], v[166:169], v[196:199], v[38:41]
	v_mfma_f32_16x16x32_bf16 v[34:37], v[180:183], v[196:199], v[34:37]
	v_mfma_f32_16x16x32_bf16 v[22:25], v[166:169], v[204:207], v[22:25]
	v_mfma_f32_16x16x32_bf16 v[18:21], v[180:183], v[204:207], v[18:21]
	v_mfma_f32_16x16x32_bf16 v[6:9], v[166:169], v[212:215], v[6:9]
	v_mfma_f32_16x16x32_bf16 v[2:5], v[180:183], v[212:215], v[2:5]
	s_setprio 2
	s_barrier
	s_add_i32 s70, s70, 2
	s_add_u32 s68, s68, 0x100
	s_addc_u32 s69, s69, 0
	s_add_u32 s12, s12, 0x100
	s_addc_u32 s13, s13, 0
	s_cmp_gt_u32 s70, 29
	s_cbranch_scc0 .LBB0_239
	s_and_b64 vcc, exec, s[20:21]
	s_cbranch_vccz .LBB0_242
	s_barrier

.LBB0_341:
	s_add_u32 s10, s12, 0xfff00080
	s_addc_u32 s11, s13, -1
	s_add_i32 s64, 0, 0x10000
	s_cmp_eq_u32 s72, 4
	s_cselect_b32 s45, s25, s11
	s_cselect_b32 s44, s68, s10
	s_cselect_b32 s43, s23, s71
	s_cselect_b32 s42, s69, s70
	s_add_i32 s65, 0, 0x14000
	v_add_u32_e32 v152, s64, v162
	v_add_u32_e32 v172, s65, v162
	ds_read_b128 v[140:143], v152
	ds_read_b128 v[144:147], v152 offset:1024
	ds_read_b128 v[148:151], v152 offset:2048
	ds_read_b128 v[152:155], v152 offset:3072
	ds_read_b128 v[156:159], v172
	ds_read_b128 v[164:167], v172 offset:1024
	ds_read_b128 v[168:171], v172 offset:2048
	ds_read_b128 v[172:175], v172 offset:3072
	v_lshl_add_u64 v[176:177], s[12:13], 0, v[138:139]
	s_add_i32 m0, s33, 0xc000
	ds_read_b128 v[180:183], v163
	ds_read_b128 v[184:187], v163 offset:1024
	ds_read_b128 v[188:191], v163 offset:2048
	ds_read_b128 v[192:195], v163 offset:3072
	ds_read_b128 v[196:199], v163 offset:4096
	ds_read_b128 v[200:203], v163 offset:5120
	ds_read_b128 v[204:207], v163 offset:6144
	ds_read_b128 v[208:211], v163 offset:7168
	global_load_lds_dwordx4 v[176:177], off
	v_lshl_add_u64 v[176:177], s[12:13], 0, v[136:137]
	s_add_i32 m0, s33, 0xe000
	s_nop 0
	global_load_lds_dwordx4 v[176:177], off
	s_waitcnt vmcnt(8)
	s_waitcnt lgkmcnt(0)
	s_barrier
	s_setprio 1
	s_waitcnt lgkmcnt(0)
	v_mfma_f32_16x16x32_bf16 v[126:129], v[140:143], v[180:183], v[126:129]
	v_mfma_f32_16x16x32_bf16 v[122:125], v[148:151], v[180:183], v[122:125]
	v_mfma_f32_16x16x32_bf16 v[118:121], v[140:143], v[188:191], v[118:121]
	v_mfma_f32_16x16x32_bf16 v[114:117], v[148:151], v[188:191], v[114:117]
	v_mfma_f32_16x16x32_bf16 v[94:97], v[140:143], v[196:199], v[94:97]
	v_mfma_f32_16x16x32_bf16 v[90:93], v[148:151], v[196:199], v[90:93]
	v_mfma_f32_16x16x32_bf16 v[78:81], v[140:143], v[204:207], v[78:81]
	v_mfma_f32_16x16x32_bf16 v[74:77], v[148:151], v[204:207], v[74:77]
	v_mfma_f32_16x16x32_bf16 v[126:129], v[144:147], v[184:187], v[126:129]
	v_mfma_f32_16x16x32_bf16 v[122:125], v[152:155], v[184:187], v[122:125]
	v_mfma_f32_16x16x32_bf16 v[118:121], v[144:147], v[192:195], v[118:121]
	v_mfma_f32_16x16x32_bf16 v[114:117], v[152:155], v[192:195], v[114:117]
	v_mfma_f32_16x16x32_bf16 v[94:97], v[144:147], v[200:203], v[94:97]
	v_mfma_f32_16x16x32_bf16 v[90:93], v[152:155], v[200:203], v[90:93]
	v_mfma_f32_16x16x32_bf16 v[78:81], v[144:147], v[208:211], v[78:81]
	v_mfma_f32_16x16x32_bf16 v[74:77], v[152:155], v[208:211], v[74:77]
	s_setprio 0
	s_setprio 1
	v_mfma_f32_16x16x32_bf16 v[110:113], v[156:159], v[180:183], v[110:113]
	v_mfma_f32_16x16x32_bf16 v[106:109], v[168:171], v[180:183], v[106:109]
	v_mfma_f32_16x16x32_bf16 v[102:105], v[156:159], v[188:191], v[102:105]
	v_mfma_f32_16x16x32_bf16 v[98:101], v[168:171], v[188:191], v[98:101]
	v_mfma_f32_16x16x32_bf16 v[86:89], v[156:159], v[196:199], v[86:89]
	v_mfma_f32_16x16x32_bf16 v[82:85], v[168:171], v[196:199], v[82:85]
	v_mfma_f32_16x16x32_bf16 v[70:73], v[156:159], v[204:207], v[70:73]
	v_mfma_f32_16x16x32_bf16 v[66:69], v[168:171], v[204:207], v[66:69]
	v_mfma_f32_16x16x32_bf16 v[110:113], v[164:167], v[184:187], v[110:113]
	v_mfma_f32_16x16x32_bf16 v[106:109], v[172:175], v[184:187], v[106:109]
	v_mfma_f32_16x16x32_bf16 v[102:105], v[164:167], v[192:195], v[102:105]
	v_mfma_f32_16x16x32_bf16 v[98:101], v[172:175], v[192:195], v[98:101]
	v_mfma_f32_16x16x32_bf16 v[86:89], v[164:167], v[200:203], v[86:89]
	v_mfma_f32_16x16x32_bf16 v[82:85], v[172:175], v[200:203], v[82:85]
	v_mfma_f32_16x16x32_bf16 v[70:73], v[164:167], v[208:211], v[70:73]
	v_mfma_f32_16x16x32_bf16 v[66:69], v[172:175], v[208:211], v[66:69]
	s_setprio 2
	s_barrier
	s_add_i32 s10, s64, s28
	v_lshl_add_u64 v[176:177], s[42:43], 0, v[0:1]
	s_mov_b32 m0, s10
	ds_read_b128 v[180:183], v163 offset:16384
	ds_read_b128 v[184:187], v163 offset:17408
	ds_read_b128 v[188:191], v163 offset:18432
	ds_read_b128 v[192:195], v163 offset:19456
	ds_read_b128 v[196:199], v163 offset:20480
	ds_read_b128 v[200:203], v163 offset:21504
	ds_read_b128 v[204:207], v163 offset:22528
	ds_read_b128 v[208:211], v163 offset:23552
	global_load_lds_dwordx4 v[176:177], off
	s_add_i32 m0, s10, 0x2000
	s_add_u32 s10, s42, 0x20000
	v_lshl_add_u64 v[178:179], s[42:43], 0, v[130:131]
	s_addc_u32 s11, s43, 0
	s_add_i32 s64, s65, s28
	global_load_lds_dwordx4 v[178:179], off
	v_lshl_add_u64 v[212:213], s[10:11], 0, v[0:1]
	s_mov_b32 m0, s64
	v_lshl_add_u64 v[214:215], s[44:45], 0, v[132:133]
	global_load_lds_dwordx4 v[212:213], off
	v_lshl_add_u64 v[212:213], s[10:11], 0, v[130:131]
	s_add_i32 m0, s64, 0x2000
	s_nop 0
	global_load_lds_dwordx4 v[212:213], off
	v_lshl_add_u64 v[212:213], s[44:45], 0, v[134:135]
	s_mov_b32 m0, s33
	s_nop 0
	global_load_lds_dwordx4 v[212:213], off
	s_mov_b32 m0, s37
	s_nop 0
	global_load_lds_dwordx4 v[214:215], off
	s_waitcnt vmcnt(8)
	s_waitcnt lgkmcnt(0)
	s_barrier
	s_setprio 1
	s_waitcnt lgkmcnt(0)
	v_mfma_f32_16x16x32_bf16 v[62:65], v[140:143], v[180:183], v[62:65]
	v_mfma_f32_16x16x32_bf16 v[58:61], v[148:151], v[180:183], v[58:61]
	v_mfma_f32_16x16x32_bf16 v[46:49], v[140:143], v[188:191], v[46:49]
	v_mfma_f32_16x16x32_bf16 v[42:45], v[148:151], v[188:191], v[42:45]
	v_mfma_f32_16x16x32_bf16 v[30:33], v[140:143], v[196:199], v[30:33]
	v_mfma_f32_16x16x32_bf16 v[26:29], v[148:151], v[196:199], v[26:29]
	v_mfma_f32_16x16x32_bf16 v[14:17], v[140:143], v[204:207], v[14:17]
	v_mfma_f32_16x16x32_bf16 v[10:13], v[148:151], v[204:207], v[10:13]
	v_mfma_f32_16x16x32_bf16 v[62:65], v[144:147], v[184:187], v[62:65]
	v_mfma_f32_16x16x32_bf16 v[58:61], v[152:155], v[184:187], v[58:61]
	v_mfma_f32_16x16x32_bf16 v[46:49], v[144:147], v[192:195], v[46:49]
	v_mfma_f32_16x16x32_bf16 v[42:45], v[152:155], v[192:195], v[42:45]
	v_mfma_f32_16x16x32_bf16 v[30:33], v[144:147], v[200:203], v[30:33]
	v_mfma_f32_16x16x32_bf16 v[26:29], v[152:155], v[200:203], v[26:29]
	v_mfma_f32_16x16x32_bf16 v[14:17], v[144:147], v[208:211], v[14:17]
	v_mfma_f32_16x16x32_bf16 v[10:13], v[152:155], v[208:211], v[10:13]
	s_setprio 0
	s_setprio 1
	v_mfma_f32_16x16x32_bf16 v[54:57], v[156:159], v[180:183], v[54:57]
	v_mfma_f32_16x16x32_bf16 v[50:53], v[168:171], v[180:183], v[50:53]
	v_mfma_f32_16x16x32_bf16 v[38:41], v[156:159], v[188:191], v[38:41]
	v_mfma_f32_16x16x32_bf16 v[34:37], v[168:171], v[188:191], v[34:37]
	v_mfma_f32_16x16x32_bf16 v[22:25], v[156:159], v[196:199], v[22:25]
	v_mfma_f32_16x16x32_bf16 v[18:21], v[168:171], v[196:199], v[18:21]
	v_mfma_f32_16x16x32_bf16 v[6:9], v[156:159], v[204:207], v[6:9]
	v_mfma_f32_16x16x32_bf16 v[2:5], v[168:171], v[204:207], v[2:5]
	v_mfma_f32_16x16x32_bf16 v[54:57], v[164:167], v[184:187], v[54:57]
	v_mfma_f32_16x16x32_bf16 v[50:53], v[172:175], v[184:187], v[50:53]
	v_mfma_f32_16x16x32_bf16 v[38:41], v[164:167], v[192:195], v[38:41]
	v_mfma_f32_16x16x32_bf16 v[34:37], v[172:175], v[192:195], v[34:37]
	v_mfma_f32_16x16x32_bf16 v[22:25], v[164:167], v[200:203], v[22:25]
	v_mfma_f32_16x16x32_bf16 v[18:21], v[172:175], v[200:203], v[18:21]
	v_mfma_f32_16x16x32_bf16 v[6:9], v[164:167], v[208:211], v[6:9]
	v_mfma_f32_16x16x32_bf16 v[2:5], v[172:175], v[208:211], v[2:5]
	s_setprio 2
	s_barrier
	s_add_i32 s64, 0, 0x18000
	s_add_i32 s65, 0, 0x1c000
	v_add_u32_e32 v152, s64, v162
	v_add_u32_e32 v172, s65, v162
	ds_read_b128 v[140:143], v152
	ds_read_b128 v[144:147], v152 offset:1024
	ds_read_b128 v[148:151], v152 offset:2048
	ds_read_b128 v[152:155], v152 offset:3072
	ds_read_b128 v[156:159], v172
	ds_read_b128 v[164:167], v172 offset:1024
	ds_read_b128 v[168:171], v172 offset:2048
	ds_read_b128 v[172:175], v172 offset:3072
	s_add_u32 s10, s44, 0x100000
	s_addc_u32 s11, s45, 0
	s_mov_b32 m0, s40
	v_lshl_add_u64 v[216:217], s[10:11], 0, v[134:135]
	ds_read_b128 v[180:183], v163 offset:32768
	ds_read_b128 v[184:187], v163 offset:33792
	ds_read_b128 v[188:191], v163 offset:34816
	ds_read_b128 v[192:195], v163 offset:35840
	ds_read_b128 v[196:199], v163 offset:36864
	ds_read_b128 v[200:203], v163 offset:37888
	ds_read_b128 v[204:207], v163 offset:38912
	ds_read_b128 v[208:211], v163 offset:39936
	global_load_lds_dwordx4 v[216:217], off
	v_lshl_add_u64 v[216:217], s[10:11], 0, v[132:133]
	s_mov_b32 m0, s41
	s_nop 0
	global_load_lds_dwordx4 v[216:217], off
	s_waitcnt vmcnt(8)
	s_waitcnt lgkmcnt(0)
	s_barrier
	s_setprio 1
	s_waitcnt lgkmcnt(0)
	v_mfma_f32_16x16x32_bf16 v[126:129], v[140:143], v[180:183], v[126:129]
	v_mfma_f32_16x16x32_bf16 v[122:125], v[148:151], v[180:183], v[122:125]
	v_mfma_f32_16x16x32_bf16 v[118:121], v[140:143], v[188:191], v[118:121]
	v_mfma_f32_16x16x32_bf16 v[114:117], v[148:151], v[188:191], v[114:117]
	v_mfma_f32_16x16x32_bf16 v[94:97], v[140:143], v[196:199], v[94:97]
	v_mfma_f32_16x16x32_bf16 v[90:93], v[148:151], v[196:199], v[90:93]
	v_mfma_f32_16x16x32_bf16 v[78:81], v[140:143], v[204:207], v[78:81]
	v_mfma_f32_16x16x32_bf16 v[74:77], v[148:151], v[204:207], v[74:77]
	v_mfma_f32_16x16x32_bf16 v[126:129], v[144:147], v[184:187], v[126:129]
	v_mfma_f32_16x16x32_bf16 v[122:125], v[152:155], v[184:187], v[122:125]
	v_mfma_f32_16x16x32_bf16 v[118:121], v[144:147], v[192:195], v[118:121]
	v_mfma_f32_16x16x32_bf16 v[114:117], v[152:155], v[192:195], v[114:117]
	v_mfma_f32_16x16x32_bf16 v[94:97], v[144:147], v[200:203], v[94:97]
	v_mfma_f32_16x16x32_bf16 v[90:93], v[152:155], v[200:203], v[90:93]
	v_mfma_f32_16x16x32_bf16 v[78:81], v[144:147], v[208:211], v[78:81]
	v_mfma_f32_16x16x32_bf16 v[74:77], v[152:155], v[208:211], v[74:77]
	s_setprio 0
	s_setprio 1
	v_mfma_f32_16x16x32_bf16 v[110:113], v[156:159], v[180:183], v[110:113]
	v_mfma_f32_16x16x32_bf16 v[106:109], v[168:171], v[180:183], v[106:109]
	v_mfma_f32_16x16x32_bf16 v[102:105], v[156:159], v[188:191], v[102:105]
	v_mfma_f32_16x16x32_bf16 v[98:101], v[168:171], v[188:191], v[98:101]
	v_mfma_f32_16x16x32_bf16 v[86:89], v[156:159], v[196:199], v[86:89]
	v_mfma_f32_16x16x32_bf16 v[82:85], v[168:171], v[196:199], v[82:85]
	v_mfma_f32_16x16x32_bf16 v[70:73], v[156:159], v[204:207], v[70:73]
	v_mfma_f32_16x16x32_bf16 v[66:69], v[168:171], v[204:207], v[66:69]
	v_mfma_f32_16x16x32_bf16 v[110:113], v[164:167], v[184:187], v[110:113]
	v_mfma_f32_16x16x32_bf16 v[106:109], v[172:175], v[184:187], v[106:109]
	v_mfma_f32_16x16x32_bf16 v[102:105], v[164:167], v[192:195], v[102:105]
	v_mfma_f32_16x16x32_bf16 v[98:101], v[172:175], v[192:195], v[98:101]
	v_mfma_f32_16x16x32_bf16 v[86:89], v[164:167], v[200:203], v[86:89]
	v_mfma_f32_16x16x32_bf16 v[82:85], v[172:175], v[200:203], v[82:85]
	v_mfma_f32_16x16x32_bf16 v[70:73], v[164:167], v[208:211], v[70:73]
	v_mfma_f32_16x16x32_bf16 v[66:69], v[172:175], v[208:211], v[66:69]
	s_setprio 2
	s_barrier
	s_add_i32 s10, s64, s28
	v_lshl_add_u64 v[176:177], v[176:177], 0, s[94:95]
	s_mov_b32 m0, s10
	ds_read_b128 v[180:183], v163 offset:49152
	ds_read_b128 v[184:187], v163 offset:50176
	ds_read_b128 v[188:191], v163 offset:51200
	ds_read_b128 v[192:195], v163 offset:52224
	ds_read_b128 v[196:199], v163 offset:53248
	ds_read_b128 v[200:203], v163 offset:54272
	ds_read_b128 v[204:207], v163 offset:55296
	ds_read_b128 v[208:211], v163 offset:56320
	global_load_lds_dwordx4 v[176:177], off
	s_add_i32 m0, s10, 0x2000
	s_add_u32 s10, s42, 0x20080
	v_lshl_add_u64 v[176:177], v[178:179], 0, s[94:95]
	s_addc_u32 s11, s43, 0
	s_add_i32 s42, s65, s28
	global_load_lds_dwordx4 v[176:177], off
	v_lshl_add_u64 v[176:177], s[10:11], 0, v[0:1]
	s_mov_b32 m0, s42
	s_nop 0
	global_load_lds_dwordx4 v[176:177], off
	v_lshl_add_u64 v[176:177], s[10:11], 0, v[130:131]
	s_add_i32 m0, s42, 0x2000
	s_nop 0
	global_load_lds_dwordx4 v[176:177], off
	v_lshl_add_u64 v[176:177], v[212:213], 0, s[94:95]
	s_mov_b32 m0, s58
	s_nop 0
	global_load_lds_dwordx4 v[176:177], off
	v_lshl_add_u64 v[176:177], v[214:215], 0, s[94:95]
	s_mov_b32 m0, s59
	s_nop 0
	global_load_lds_dwordx4 v[176:177], off
	s_waitcnt vmcnt(8)
	s_waitcnt lgkmcnt(0)
	s_barrier
	s_setprio 1
	s_waitcnt lgkmcnt(0)
	v_mfma_f32_16x16x32_bf16 v[62:65], v[140:143], v[180:183], v[62:65]
	v_mfma_f32_16x16x32_bf16 v[58:61], v[148:151], v[180:183], v[58:61]
	v_mfma_f32_16x16x32_bf16 v[46:49], v[140:143], v[188:191], v[46:49]
	v_mfma_f32_16x16x32_bf16 v[42:45], v[148:151], v[188:191], v[42:45]
	v_mfma_f32_16x16x32_bf16 v[30:33], v[140:143], v[196:199], v[30:33]
	v_mfma_f32_16x16x32_bf16 v[26:29], v[148:151], v[196:199], v[26:29]
	v_mfma_f32_16x16x32_bf16 v[14:17], v[140:143], v[204:207], v[14:17]
	v_mfma_f32_16x16x32_bf16 v[10:13], v[148:151], v[204:207], v[10:13]
	v_mfma_f32_16x16x32_bf16 v[62:65], v[144:147], v[184:187], v[62:65]
	v_mfma_f32_16x16x32_bf16 v[58:61], v[152:155], v[184:187], v[58:61]
	v_mfma_f32_16x16x32_bf16 v[46:49], v[144:147], v[192:195], v[46:49]
	v_mfma_f32_16x16x32_bf16 v[42:45], v[152:155], v[192:195], v[42:45]
	v_mfma_f32_16x16x32_bf16 v[30:33], v[144:147], v[200:203], v[30:33]
	v_mfma_f32_16x16x32_bf16 v[26:29], v[152:155], v[200:203], v[26:29]
	v_mfma_f32_16x16x32_bf16 v[14:17], v[144:147], v[208:211], v[14:17]
	v_mfma_f32_16x16x32_bf16 v[10:13], v[152:155], v[208:211], v[10:13]
	s_setprio 0
	s_setprio 1
	v_mfma_f32_16x16x32_bf16 v[54:57], v[156:159], v[180:183], v[54:57]
	v_mfma_f32_16x16x32_bf16 v[50:53], v[168:171], v[180:183], v[50:53]
	v_mfma_f32_16x16x32_bf16 v[38:41], v[156:159], v[188:191], v[38:41]
	v_mfma_f32_16x16x32_bf16 v[34:37], v[168:171], v[188:191], v[34:37]
	v_mfma_f32_16x16x32_bf16 v[22:25], v[156:159], v[196:199], v[22:25]
	v_mfma_f32_16x16x32_bf16 v[18:21], v[168:171], v[196:199], v[18:21]
	v_mfma_f32_16x16x32_bf16 v[6:9], v[156:159], v[204:207], v[6:9]
	v_mfma_f32_16x16x32_bf16 v[2:5], v[168:171], v[204:207], v[2:5]
	v_mfma_f32_16x16x32_bf16 v[54:57], v[164:167], v[184:187], v[54:57]
	v_mfma_f32_16x16x32_bf16 v[50:53], v[172:175], v[184:187], v[50:53]
	v_mfma_f32_16x16x32_bf16 v[38:41], v[164:167], v[192:195], v[38:41]
	v_mfma_f32_16x16x32_bf16 v[34:37], v[172:175], v[192:195], v[34:37]
	v_mfma_f32_16x16x32_bf16 v[22:25], v[164:167], v[200:203], v[22:25]
	v_mfma_f32_16x16x32_bf16 v[18:21], v[172:175], v[200:203], v[18:21]
	v_mfma_f32_16x16x32_bf16 v[6:9], v[164:167], v[208:211], v[6:9]
	v_mfma_f32_16x16x32_bf16 v[2:5], v[172:175], v[208:211], v[2:5]
	s_setprio 2
	s_barrier
	s_add_i32 s72, s72, 2
	s_add_u32 s70, s70, 0x100
	s_addc_u32 s71, s71, 0
	s_add_u32 s12, s12, 0x100
	s_addc_u32 s13, s13, 0
	s_cmp_gt_u32 s72, 5
	s_cbranch_scc0 .LBB0_341
	s_and_b64 vcc, exec, s[20:21]
	s_cbranch_vccz .LBB0_344
	s_barrier

.LBB0_360:
	s_ashr_i32 s57, s56, 31
	s_lshl_b64 s[10:11], s[56:57], 21
	s_add_u32 s60, s0, s10
	s_addc_u32 s61, s1, s11
	s_and_b64 s[10:11], s[12:13], exec
	s_cselect_b32 s73, s61, s15
	s_cselect_b32 s72, s60, s14
	s_ashr_i32 s45, s44, 31
	s_lshl_b64 s[10:11], s[44:45], 17
	s_add_u32 s62, s33, s10
	s_addc_u32 s63, s37, s11
	s_and_b64 s[10:11], s[12:13], exec
	s_cselect_b32 s71, s63, s69
	s_cselect_b32 s70, s62, s68
	s_add_i32 vcc_hi, 0, 0x10000
	s_add_i32 s91, 0, 0x14000
	v_add_u32_e32 v0, vcc_hi, v208
	v_add_u32_e32 v216, s91, v208
	ds_read_b128 v[2:5], v0
	ds_read_b128 v[6:9], v0 offset:1024
	ds_read_b128 v[10:13], v0 offset:2048
	ds_read_b128 v[14:17], v0 offset:3072
	ds_read_b128 v[18:21], v216
	ds_read_b128 v[22:25], v216 offset:1024
	ds_read_b128 v[26:29], v216 offset:2048
	ds_read_b128 v[30:33], v216 offset:3072
	v_mov_b32_e32 v237, 0xc00
	s_mov_b32 s80, s54
	s_add_u32 s64, s14, 0x100080
	s_addc_u32 s65, s15, 0
	s_add_i32 s11, s40, 0xc000
	v_lshl_add_u64 v[66:67], s[64:65], 0, v[136:137]
	s_mov_b32 m0, s11
	s_add_i32 s45, s40, 0xe000
	ds_read_b128 v[34:37], v209
	ds_read_b128 v[38:41], v209 offset:1024
	ds_read_b128 v[42:45], v209 offset:2048
	ds_read_b128 v[46:49], v209 offset:3072
	ds_read_b128 v[50:53], v209 offset:4096
	ds_read_b128 v[54:57], v209 offset:5120
	ds_read_b128 v[58:61], v209 offset:6144
	ds_read_b128 v[62:65], v209 offset:7168
	global_load_lds_dwordx4 v[66:67], off
	v_lshl_add_u64 v[66:67], s[64:65], 0, v[132:133]
	s_mov_b32 m0, s45
	s_nop 0
	global_load_lds_dwordx4 v[66:67], off
	s_waitcnt vmcnt(8)
	s_waitcnt lgkmcnt(0)
	s_barrier
	s_setprio 1
	s_waitcnt lgkmcnt(0)
	v_mfma_f32_16x16x32_bf16 v[66:69], v[2:5], v[34:37], 0
	v_mfma_f32_16x16x32_bf16 v[70:73], v[10:13], v[34:37], 0
	v_mfma_f32_16x16x32_bf16 v[74:77], v[2:5], v[42:45], 0
	v_mfma_f32_16x16x32_bf16 v[78:81], v[10:13], v[42:45], 0
	v_mfma_f32_16x16x32_bf16 v[82:85], v[2:5], v[50:53], 0
	v_mfma_f32_16x16x32_bf16 v[86:89], v[10:13], v[50:53], 0
	v_mfma_f32_16x16x32_bf16 v[90:93], v[2:5], v[58:61], 0
	v_mfma_f32_16x16x32_bf16 v[94:97], v[10:13], v[58:61], 0
	v_mfma_f32_16x16x32_bf16 v[66:69], v[6:9], v[38:41], v[66:69]
	v_mfma_f32_16x16x32_bf16 v[70:73], v[14:17], v[38:41], v[70:73]
	v_mfma_f32_16x16x32_bf16 v[74:77], v[6:9], v[46:49], v[74:77]
	v_mfma_f32_16x16x32_bf16 v[78:81], v[14:17], v[46:49], v[78:81]
	v_mfma_f32_16x16x32_bf16 v[82:85], v[6:9], v[54:57], v[82:85]
	v_mfma_f32_16x16x32_bf16 v[86:89], v[14:17], v[54:57], v[86:89]
	v_mfma_f32_16x16x32_bf16 v[90:93], v[6:9], v[62:65], v[90:93]
	v_mfma_f32_16x16x32_bf16 v[94:97], v[14:17], v[62:65], v[94:97]
	s_setprio 0
	s_setprio 1
	v_mfma_f32_16x16x32_bf16 v[98:101], v[18:21], v[34:37], 0
	v_mfma_f32_16x16x32_bf16 v[34:37], v[26:29], v[34:37], 0
	v_mfma_f32_16x16x32_bf16 v[98:101], v[22:25], v[38:41], v[98:101]
	v_mfma_f32_16x16x32_bf16 v[34:37], v[30:33], v[38:41], v[34:37]
	v_mfma_f32_16x16x32_bf16 v[38:41], v[18:21], v[42:45], 0
	v_mfma_f32_16x16x32_bf16 v[42:45], v[26:29], v[42:45], 0
	v_mfma_f32_16x16x32_bf16 v[38:41], v[22:25], v[46:49], v[38:41]
	v_mfma_f32_16x16x32_bf16 v[42:45], v[30:33], v[46:49], v[42:45]
	v_mfma_f32_16x16x32_bf16 v[46:49], v[18:21], v[50:53], 0
	v_mfma_f32_16x16x32_bf16 v[50:53], v[26:29], v[50:53], 0
	v_mfma_f32_16x16x32_bf16 v[46:49], v[22:25], v[54:57], v[46:49]
	v_mfma_f32_16x16x32_bf16 v[50:53], v[30:33], v[54:57], v[50:53]
	v_mfma_f32_16x16x32_bf16 v[54:57], v[18:21], v[58:61], 0
	v_mfma_f32_16x16x32_bf16 v[58:61], v[26:29], v[58:61], 0
	v_mfma_f32_16x16x32_bf16 v[54:57], v[22:25], v[62:65], v[54:57]
	v_mfma_f32_16x16x32_bf16 v[58:61], v[30:33], v[62:65], v[58:61]
	s_setprio 2
	s_barrier
	s_add_i32 vcc_hi, vcc_hi, s28
	v_lshl_add_u64 v[174:175], s[68:69], 0, v[134:135]
	s_add_i32 s57, vcc_hi, 0x2000
	v_lshl_add_u64 v[138:139], v[174:175], 0, s[96:97]
	s_mov_b32 m0, vcc_hi
	v_lshl_add_u64 v[176:177], s[68:69], 0, v[130:131]
	s_add_u32 s64, s68, 0x10100
	ds_read_b128 v[62:65], v209 offset:16384
	ds_read_b128 v[102:105], v209 offset:17408
	ds_read_b128 v[106:109], v209 offset:18432
	ds_read_b128 v[110:113], v209 offset:19456
	ds_read_b128 v[114:117], v209 offset:20480
	ds_read_b128 v[118:121], v209 offset:21504
	ds_read_b128 v[122:125], v209 offset:22528
	ds_read_b128 v[126:129], v209 offset:23552
	global_load_lds_dwordx4 v[138:139], off
	v_lshl_add_u64 v[138:139], v[176:177], 0, s[96:97]
	s_mov_b32 m0, s57
	s_addc_u32 s65, s69, 0
	s_add_i32 s91, s91, s28
	global_load_lds_dwordx4 v[138:139], off
	v_lshl_add_u64 v[138:139], s[64:65], 0, v[134:135]
	s_mov_b32 m0, s91
	s_add_i32 vcc_lo, s91, 0x2000
	global_load_lds_dwordx4 v[138:139], off
	v_lshl_add_u64 v[138:139], s[64:65], 0, v[130:131]
	s_mov_b32 m0, vcc_lo
	v_lshl_add_u64 v[178:179], s[14:15], 0, v[136:137]
	global_load_lds_dwordx4 v[138:139], off
	v_lshl_add_u64 v[138:139], v[178:179], 0, s[96:97]
	s_mov_b32 m0, s40
	v_lshl_add_u64 v[204:205], s[14:15], 0, v[132:133]
	global_load_lds_dwordx4 v[138:139], off
	v_lshl_add_u64 v[138:139], v[204:205], 0, s[96:97]
	s_mov_b32 m0, s41
	s_nop 0
	global_load_lds_dwordx4 v[138:139], off
	s_waitcnt vmcnt(8)
	s_waitcnt lgkmcnt(0)
	s_barrier
	s_setprio 1
	s_waitcnt lgkmcnt(0)
	v_mfma_f32_16x16x32_bf16 v[138:141], v[2:5], v[62:65], 0
	v_mfma_f32_16x16x32_bf16 v[146:149], v[2:5], v[106:109], 0
	v_mfma_f32_16x16x32_bf16 v[154:157], v[2:5], v[114:117], 0
	v_mfma_f32_16x16x32_bf16 v[2:5], v[2:5], v[122:125], 0
	v_mfma_f32_16x16x32_bf16 v[138:141], v[6:9], v[102:105], v[138:141]
	v_mfma_f32_16x16x32_bf16 v[146:149], v[6:9], v[110:113], v[146:149]
	v_mfma_f32_16x16x32_bf16 v[154:157], v[6:9], v[118:121], v[154:157]
	v_mfma_f32_16x16x32_bf16 v[2:5], v[6:9], v[126:129], v[2:5]
	v_mfma_f32_16x16x32_bf16 v[6:9], v[10:13], v[122:125], 0
	v_mfma_f32_16x16x32_bf16 v[142:145], v[10:13], v[62:65], 0
	v_mfma_f32_16x16x32_bf16 v[150:153], v[10:13], v[106:109], 0
	v_mfma_f32_16x16x32_bf16 v[158:161], v[10:13], v[114:117], 0
	v_mfma_f32_16x16x32_bf16 v[6:9], v[14:17], v[126:129], v[6:9]
	v_mfma_f32_16x16x32_bf16 v[142:145], v[14:17], v[102:105], v[142:145]
	v_mfma_f32_16x16x32_bf16 v[150:153], v[14:17], v[110:113], v[150:153]
	v_mfma_f32_16x16x32_bf16 v[158:161], v[14:17], v[118:121], v[158:161]
	s_setprio 0
	s_setprio 1
	v_mfma_f32_16x16x32_bf16 v[10:13], v[18:21], v[62:65], 0
	v_mfma_f32_16x16x32_bf16 v[14:17], v[26:29], v[62:65], 0
	v_mfma_f32_16x16x32_bf16 v[10:13], v[22:25], v[102:105], v[10:13]
	v_mfma_f32_16x16x32_bf16 v[14:17], v[30:33], v[102:105], v[14:17]
	v_mfma_f32_16x16x32_bf16 v[62:65], v[18:21], v[106:109], 0
	v_mfma_f32_16x16x32_bf16 v[102:105], v[26:29], v[106:109], 0
	v_mfma_f32_16x16x32_bf16 v[106:109], v[18:21], v[114:117], 0
	v_mfma_f32_16x16x32_bf16 v[18:21], v[18:21], v[122:125], 0
	v_mfma_f32_16x16x32_bf16 v[62:65], v[22:25], v[110:113], v[62:65]
	v_mfma_f32_16x16x32_bf16 v[102:105], v[30:33], v[110:113], v[102:105]
	v_mfma_f32_16x16x32_bf16 v[106:109], v[22:25], v[118:121], v[106:109]
	v_mfma_f32_16x16x32_bf16 v[110:113], v[26:29], v[114:117], 0
	v_mfma_f32_16x16x32_bf16 v[18:21], v[22:25], v[126:129], v[18:21]
	v_mfma_f32_16x16x32_bf16 v[22:25], v[26:29], v[122:125], 0
	v_mfma_f32_16x16x32_bf16 v[110:113], v[30:33], v[118:121], v[110:113]
	v_mfma_f32_16x16x32_bf16 v[22:25], v[30:33], v[126:129], v[22:25]
	s_setprio 2
	s_barrier
	s_add_i32 s10, 0, 0x18000
	s_add_i32 s16, 0, 0x1c000
	v_add_u32_e32 v226, s10, v208
	v_add_u32_e32 v227, s16, v208
	ds_read_b128 v[26:29], v226
	ds_read_b128 v[30:33], v226 offset:1024
	ds_read_b128 v[114:117], v226 offset:2048
	ds_read_b128 v[118:121], v226 offset:3072
	ds_read_b128 v[122:125], v227
	ds_read_b128 v[126:129], v227 offset:1024
	ds_read_b128 v[162:165], v227 offset:2048
	ds_read_b128 v[166:169], v227 offset:3072
	s_add_u32 s64, s14, 0x100100
	s_addc_u32 s65, s15, 0
	s_mov_b32 m0, s48
	v_lshl_add_u64 v[214:215], s[64:65], 0, v[136:137]
	ds_read_b128 v[170:173], v209 offset:32768
	ds_read_b128 v[180:183], v209 offset:33792
	ds_read_b128 v[184:187], v209 offset:34816
	ds_read_b128 v[188:191], v209 offset:35840
	ds_read_b128 v[192:195], v209 offset:36864
	ds_read_b128 v[196:199], v209 offset:37888
	ds_read_b128 v[200:203], v209 offset:38912
	ds_read_b128 v[210:213], v209 offset:39936
	global_load_lds_dwordx4 v[214:215], off
	v_lshl_add_u64 v[214:215], s[64:65], 0, v[132:133]
	s_mov_b32 m0, s52
	s_nop 0
	global_load_lds_dwordx4 v[214:215], off
	s_waitcnt vmcnt(8)
	s_waitcnt lgkmcnt(0)
	s_barrier
	s_setprio 1
	s_waitcnt lgkmcnt(0)
	v_mfma_f32_16x16x32_bf16 v[66:69], v[26:29], v[170:173], v[66:69]
	v_mfma_f32_16x16x32_bf16 v[70:73], v[114:117], v[170:173], v[70:73]
	v_mfma_f32_16x16x32_bf16 v[74:77], v[26:29], v[184:187], v[74:77]
	v_mfma_f32_16x16x32_bf16 v[78:81], v[114:117], v[184:187], v[78:81]
	v_mfma_f32_16x16x32_bf16 v[82:85], v[26:29], v[192:195], v[82:85]
	v_mfma_f32_16x16x32_bf16 v[86:89], v[114:117], v[192:195], v[86:89]
	v_mfma_f32_16x16x32_bf16 v[90:93], v[26:29], v[200:203], v[90:93]
	v_mfma_f32_16x16x32_bf16 v[94:97], v[114:117], v[200:203], v[94:97]
	v_mfma_f32_16x16x32_bf16 v[66:69], v[30:33], v[180:183], v[66:69]
	v_mfma_f32_16x16x32_bf16 v[70:73], v[118:121], v[180:183], v[70:73]
	v_mfma_f32_16x16x32_bf16 v[74:77], v[30:33], v[188:191], v[74:77]
	v_mfma_f32_16x16x32_bf16 v[78:81], v[118:121], v[188:191], v[78:81]
	v_mfma_f32_16x16x32_bf16 v[82:85], v[30:33], v[196:199], v[82:85]
	v_mfma_f32_16x16x32_bf16 v[86:89], v[118:121], v[196:199], v[86:89]
	v_mfma_f32_16x16x32_bf16 v[90:93], v[30:33], v[210:213], v[90:93]
	v_mfma_f32_16x16x32_bf16 v[94:97], v[118:121], v[210:213], v[94:97]
	s_setprio 0
	s_setprio 1
	v_mfma_f32_16x16x32_bf16 v[98:101], v[122:125], v[170:173], v[98:101]
	v_mfma_f32_16x16x32_bf16 v[34:37], v[162:165], v[170:173], v[34:37]
	v_mfma_f32_16x16x32_bf16 v[38:41], v[122:125], v[184:187], v[38:41]
	v_mfma_f32_16x16x32_bf16 v[42:45], v[162:165], v[184:187], v[42:45]
	v_mfma_f32_16x16x32_bf16 v[46:49], v[122:125], v[192:195], v[46:49]
	v_mfma_f32_16x16x32_bf16 v[50:53], v[162:165], v[192:195], v[50:53]
	v_mfma_f32_16x16x32_bf16 v[54:57], v[122:125], v[200:203], v[54:57]
	v_mfma_f32_16x16x32_bf16 v[58:61], v[162:165], v[200:203], v[58:61]
	v_mfma_f32_16x16x32_bf16 v[98:101], v[126:129], v[180:183], v[98:101]
	v_mfma_f32_16x16x32_bf16 v[34:37], v[166:169], v[180:183], v[34:37]
	v_mfma_f32_16x16x32_bf16 v[38:41], v[126:129], v[188:191], v[38:41]
	v_mfma_f32_16x16x32_bf16 v[42:45], v[166:169], v[188:191], v[42:45]
	v_mfma_f32_16x16x32_bf16 v[46:49], v[126:129], v[196:199], v[46:49]
	v_mfma_f32_16x16x32_bf16 v[50:53], v[166:169], v[196:199], v[50:53]
	v_mfma_f32_16x16x32_bf16 v[54:57], v[126:129], v[210:213], v[54:57]
	v_mfma_f32_16x16x32_bf16 v[58:61], v[166:169], v[210:213], v[58:61]
	s_setprio 2
	s_barrier
	s_add_i32 s10, s10, s28
	s_mov_b64 s[54:55], 0x180
	s_add_i32 s64, s10, 0x2000
	v_lshl_add_u64 v[174:175], v[174:175], 0, s[54:55]
	s_mov_b32 m0, s10
	s_add_u32 s24, s68, 0x10180
	ds_read_b128 v[170:173], v209 offset:49152
	ds_read_b128 v[180:183], v209 offset:50176
	ds_read_b128 v[184:187], v209 offset:51200
	ds_read_b128 v[188:191], v209 offset:52224
	ds_read_b128 v[192:195], v209 offset:53248
	ds_read_b128 v[196:199], v209 offset:54272
	ds_read_b128 v[200:203], v209 offset:55296
	ds_read_b128 v[210:213], v209 offset:56320
	global_load_lds_dwordx4 v[174:175], off
	v_lshl_add_u64 v[174:175], v[176:177], 0, s[54:55]
	s_mov_b32 m0, s64
	s_addc_u32 s25, s69, 0
	s_add_i32 s16, s16, s28
	global_load_lds_dwordx4 v[174:175], off
	v_lshl_add_u64 v[174:175], s[24:25], 0, v[134:135]
	s_mov_b32 m0, s16
	s_add_i32 s17, s16, 0x2000
	global_load_lds_dwordx4 v[174:175], off
	v_lshl_add_u64 v[174:175], s[24:25], 0, v[130:131]
	s_mov_b32 m0, s17
	s_nop 0
	global_load_lds_dwordx4 v[174:175], off
	v_lshl_add_u64 v[174:175], v[178:179], 0, s[54:55]
	s_mov_b32 m0, s74
	s_nop 0
	global_load_lds_dwordx4 v[174:175], off
	v_lshl_add_u64 v[174:175], v[204:205], 0, s[54:55]
	s_mov_b32 m0, s75
	s_nop 0
	global_load_lds_dwordx4 v[174:175], off
	s_waitcnt vmcnt(8)
	s_waitcnt lgkmcnt(0)
	s_barrier
	s_setprio 1
	s_waitcnt lgkmcnt(0)
	v_mfma_f32_16x16x32_bf16 v[2:5], v[26:29], v[200:203], v[2:5]
	v_mfma_f32_16x16x32_bf16 v[6:9], v[114:117], v[200:203], v[6:9]
	v_mfma_f32_16x16x32_bf16 v[138:141], v[26:29], v[170:173], v[138:141]
	v_mfma_f32_16x16x32_bf16 v[142:145], v[114:117], v[170:173], v[142:145]
	v_mfma_f32_16x16x32_bf16 v[146:149], v[26:29], v[184:187], v[146:149]
	v_mfma_f32_16x16x32_bf16 v[150:153], v[114:117], v[184:187], v[150:153]
	v_mfma_f32_16x16x32_bf16 v[154:157], v[26:29], v[192:195], v[154:157]
	v_mfma_f32_16x16x32_bf16 v[158:161], v[114:117], v[192:195], v[158:161]
	v_mfma_f32_16x16x32_bf16 v[2:5], v[30:33], v[210:213], v[2:5]
	v_mfma_f32_16x16x32_bf16 v[6:9], v[118:121], v[210:213], v[6:9]
	v_mfma_f32_16x16x32_bf16 v[138:141], v[30:33], v[180:183], v[138:141]
	v_mfma_f32_16x16x32_bf16 v[142:145], v[118:121], v[180:183], v[142:145]
	v_mfma_f32_16x16x32_bf16 v[146:149], v[30:33], v[188:191], v[146:149]
	v_mfma_f32_16x16x32_bf16 v[150:153], v[118:121], v[188:191], v[150:153]
	v_mfma_f32_16x16x32_bf16 v[154:157], v[30:33], v[196:199], v[154:157]
	v_mfma_f32_16x16x32_bf16 v[158:161], v[118:121], v[196:199], v[158:161]
	s_setprio 0
	s_setprio 1
	v_mfma_f32_16x16x32_bf16 v[10:13], v[122:125], v[170:173], v[10:13]
	v_mfma_f32_16x16x32_bf16 v[14:17], v[162:165], v[170:173], v[14:17]
	v_mfma_f32_16x16x32_bf16 v[26:29], v[122:125], v[184:187], v[62:65]
	v_mfma_f32_16x16x32_bf16 v[30:33], v[162:165], v[184:187], v[102:105]
	v_mfma_f32_16x16x32_bf16 v[62:65], v[122:125], v[192:195], v[106:109]
	v_mfma_f32_16x16x32_bf16 v[102:105], v[162:165], v[192:195], v[110:113]
	v_mfma_f32_16x16x32_bf16 v[18:21], v[122:125], v[200:203], v[18:21]
	v_mfma_f32_16x16x32_bf16 v[22:25], v[162:165], v[200:203], v[22:25]
	v_mfma_f32_16x16x32_bf16 v[10:13], v[126:129], v[180:183], v[10:13]
	v_mfma_f32_16x16x32_bf16 v[14:17], v[166:169], v[180:183], v[14:17]
	v_mfma_f32_16x16x32_bf16 v[26:29], v[126:129], v[188:191], v[26:29]
	v_mfma_f32_16x16x32_bf16 v[30:33], v[166:169], v[188:191], v[30:33]
	v_mfma_f32_16x16x32_bf16 v[62:65], v[126:129], v[196:199], v[62:65]
	v_mfma_f32_16x16x32_bf16 v[102:105], v[166:169], v[196:199], v[102:105]
	v_mfma_f32_16x16x32_bf16 v[18:21], v[126:129], v[210:213], v[18:21]
	v_mfma_f32_16x16x32_bf16 v[22:25], v[166:169], v[210:213], v[22:25]
	s_setprio 2
	s_barrier
	ds_read_b128 v[106:109], v0
	ds_read_b128 v[110:113], v0 offset:1024
	ds_read_b128 v[114:117], v0 offset:2048
	ds_read_b128 v[118:121], v0 offset:3072
	ds_read_b128 v[122:125], v216
	ds_read_b128 v[126:129], v216 offset:1024
	ds_read_b128 v[162:165], v216 offset:2048
	ds_read_b128 v[166:169], v216 offset:3072
	s_add_u32 s14, s14, 0x100180
	s_addc_u32 s15, s15, 0
	s_mov_b32 m0, s11
	v_lshl_add_u64 v[174:175], s[14:15], 0, v[136:137]
	ds_read_b128 v[170:173], v209
	ds_read_b128 v[180:183], v209 offset:1024
	ds_read_b128 v[184:187], v209 offset:2048
	ds_read_b128 v[188:191], v209 offset:3072
	ds_read_b128 v[192:195], v209 offset:4096
	ds_read_b128 v[196:199], v209 offset:5120
	ds_read_b128 v[200:203], v209 offset:6144
	ds_read_b128 v[210:213], v209 offset:7168
	global_load_lds_dwordx4 v[174:175], off
	v_lshl_add_u64 v[174:175], s[14:15], 0, v[132:133]
	s_mov_b32 m0, s45
	s_nop 0
	global_load_lds_dwordx4 v[174:175], off
	s_waitcnt vmcnt(8)
	s_waitcnt lgkmcnt(0)
	s_barrier
	s_setprio 1
	s_waitcnt lgkmcnt(0)
	v_mfma_f32_16x16x32_bf16 v[66:69], v[106:109], v[170:173], v[66:69]
	v_mfma_f32_16x16x32_bf16 v[70:73], v[114:117], v[170:173], v[70:73]
	v_mfma_f32_16x16x32_bf16 v[74:77], v[106:109], v[184:187], v[74:77]
	v_mfma_f32_16x16x32_bf16 v[78:81], v[114:117], v[184:187], v[78:81]
	v_mfma_f32_16x16x32_bf16 v[82:85], v[106:109], v[192:195], v[82:85]
	v_mfma_f32_16x16x32_bf16 v[86:89], v[114:117], v[192:195], v[86:89]
	v_mfma_f32_16x16x32_bf16 v[90:93], v[106:109], v[200:203], v[90:93]
	v_mfma_f32_16x16x32_bf16 v[66:69], v[110:113], v[180:183], v[66:69]
	v_mfma_f32_16x16x32_bf16 v[70:73], v[118:121], v[180:183], v[70:73]
	v_mfma_f32_16x16x32_bf16 v[74:77], v[110:113], v[188:191], v[74:77]
	v_mfma_f32_16x16x32_bf16 v[78:81], v[118:121], v[188:191], v[78:81]
	v_mfma_f32_16x16x32_bf16 v[82:85], v[110:113], v[196:199], v[82:85]
	v_mfma_f32_16x16x32_bf16 v[86:89], v[118:121], v[196:199], v[86:89]
	v_mfma_f32_16x16x32_bf16 v[90:93], v[110:113], v[210:213], v[90:93]
	v_mfma_f32_16x16x32_bf16 v[94:97], v[114:117], v[200:203], v[94:97]
	v_mfma_f32_16x16x32_bf16 v[214:217], v[118:121], v[210:213], v[94:97]
	s_setprio 0
	s_setprio 1
	v_mfma_f32_16x16x32_bf16 v[94:97], v[122:125], v[170:173], v[98:101]
	v_mfma_f32_16x16x32_bf16 v[34:37], v[162:165], v[170:173], v[34:37]
	v_mfma_f32_16x16x32_bf16 v[38:41], v[122:125], v[184:187], v[38:41]
	v_mfma_f32_16x16x32_bf16 v[42:45], v[162:165], v[184:187], v[42:45]
	v_mfma_f32_16x16x32_bf16 v[46:49], v[122:125], v[192:195], v[46:49]
	v_mfma_f32_16x16x32_bf16 v[50:53], v[162:165], v[192:195], v[50:53]
	v_mfma_f32_16x16x32_bf16 v[54:57], v[122:125], v[200:203], v[54:57]
	v_mfma_f32_16x16x32_bf16 v[58:61], v[162:165], v[200:203], v[58:61]
	v_mfma_f32_16x16x32_bf16 v[98:101], v[126:129], v[180:183], v[94:97]
	v_mfma_f32_16x16x32_bf16 v[34:37], v[166:169], v[180:183], v[34:37]
	v_mfma_f32_16x16x32_bf16 v[38:41], v[126:129], v[188:191], v[38:41]
	v_mfma_f32_16x16x32_bf16 v[42:45], v[166:169], v[188:191], v[42:45]
	v_mfma_f32_16x16x32_bf16 v[46:49], v[126:129], v[196:199], v[46:49]
	v_mfma_f32_16x16x32_bf16 v[50:53], v[166:169], v[196:199], v[50:53]
	v_mfma_f32_16x16x32_bf16 v[54:57], v[126:129], v[210:213], v[54:57]
	v_mfma_f32_16x16x32_bf16 v[58:61], v[166:169], v[210:213], v[58:61]
	s_setprio 2
	s_barrier
	s_mov_b32 m0, vcc_hi
	v_lshl_add_u64 v[178:179], s[70:71], 0, v[134:135]
	s_add_u32 s14, s70, 0x10000
	ds_read_b128 v[94:97], v209 offset:16384
	ds_read_b128 v[170:173], v209 offset:17408
	ds_read_b128 v[180:183], v209 offset:18432
	ds_read_b128 v[184:187], v209 offset:19456
	ds_read_b128 v[188:191], v209 offset:20480
	ds_read_b128 v[192:195], v209 offset:21504
	ds_read_b128 v[196:199], v209 offset:22528
	ds_read_b128 v[200:203], v209 offset:23552
	global_load_lds_dwordx4 v[178:179], off
	v_lshl_add_u64 v[204:205], s[70:71], 0, v[130:131]
	s_mov_b32 m0, s57
	s_addc_u32 s15, s71, 0
	global_load_lds_dwordx4 v[204:205], off
	v_lshl_add_u64 v[174:175], s[14:15], 0, v[134:135]
	s_mov_b32 m0, s91
	v_lshl_add_u64 v[230:231], s[72:73], 0, v[136:137]
	global_load_lds_dwordx4 v[174:175], off
	v_lshl_add_u64 v[174:175], s[14:15], 0, v[130:131]
	s_mov_b32 m0, vcc_lo
	v_lshl_add_u64 v[234:235], s[72:73], 0, v[132:133]
	global_load_lds_dwordx4 v[174:175], off
	s_mov_b32 m0, s40
	s_nop 0
	global_load_lds_dwordx4 v[230:231], off
	s_mov_b32 m0, s41
	s_nop 0
	global_load_lds_dwordx4 v[234:235], off
	s_waitcnt vmcnt(8)
	s_waitcnt lgkmcnt(0)
	s_barrier
	s_setprio 1
	s_waitcnt lgkmcnt(0)
	v_mfma_f32_16x16x32_bf16 v[2:5], v[106:109], v[196:199], v[2:5]
	v_mfma_f32_16x16x32_bf16 v[138:141], v[106:109], v[94:97], v[138:141]
	v_mfma_f32_16x16x32_bf16 v[142:145], v[114:117], v[94:97], v[142:145]
	v_mfma_f32_16x16x32_bf16 v[146:149], v[106:109], v[180:183], v[146:149]
	v_mfma_f32_16x16x32_bf16 v[150:153], v[114:117], v[180:183], v[150:153]
	v_mfma_f32_16x16x32_bf16 v[154:157], v[106:109], v[188:191], v[154:157]
	v_mfma_f32_16x16x32_bf16 v[158:161], v[114:117], v[188:191], v[158:161]
	v_mfma_f32_16x16x32_bf16 v[210:213], v[110:113], v[200:203], v[2:5]
	v_mfma_f32_16x16x32_bf16 v[2:5], v[114:117], v[196:199], v[6:9]
	v_mfma_f32_16x16x32_bf16 v[138:141], v[110:113], v[170:173], v[138:141]
	v_mfma_f32_16x16x32_bf16 v[142:145], v[118:121], v[170:173], v[142:145]
	v_mfma_f32_16x16x32_bf16 v[146:149], v[110:113], v[184:187], v[146:149]
	v_mfma_f32_16x16x32_bf16 v[150:153], v[118:121], v[184:187], v[150:153]
	v_mfma_f32_16x16x32_bf16 v[154:157], v[110:113], v[192:195], v[154:157]
	v_mfma_f32_16x16x32_bf16 v[158:161], v[118:121], v[192:195], v[158:161]
	v_mfma_f32_16x16x32_bf16 v[218:221], v[118:121], v[200:203], v[2:5]
	s_setprio 0
	s_setprio 1
	v_mfma_f32_16x16x32_bf16 v[2:5], v[122:125], v[94:97], v[10:13]
	v_mfma_f32_16x16x32_bf16 v[222:225], v[126:129], v[170:173], v[2:5]
	v_mfma_f32_16x16x32_bf16 v[2:5], v[162:165], v[94:97], v[14:17]
	v_mfma_f32_16x16x32_bf16 v[170:173], v[166:169], v[170:173], v[2:5]
	v_mfma_f32_16x16x32_bf16 v[2:5], v[122:125], v[180:183], v[26:29]
	v_mfma_f32_16x16x32_bf16 v[250:253], v[126:129], v[184:187], v[2:5]
	v_mfma_f32_16x16x32_bf16 v[2:5], v[162:165], v[180:183], v[30:33]
	v_mfma_f32_16x16x32_bf16 v[180:183], v[166:169], v[184:187], v[2:5]
	v_mfma_f32_16x16x32_bf16 v[2:5], v[122:125], v[188:191], v[62:65]
	v_mfma_f32_16x16x32_bf16 v[62:65], v[126:129], v[192:195], v[2:5]
	v_mfma_f32_16x16x32_bf16 v[2:5], v[162:165], v[188:191], v[102:105]
	v_mfma_f32_16x16x32_bf16 v[184:187], v[166:169], v[192:195], v[2:5]
	v_mfma_f32_16x16x32_bf16 v[2:5], v[122:125], v[196:199], v[18:21]
	v_mfma_f32_16x16x32_bf16 v[188:191], v[126:129], v[200:203], v[2:5]
	v_mfma_f32_16x16x32_bf16 v[2:5], v[162:165], v[196:199], v[22:25]
	v_mfma_f32_16x16x32_bf16 v[162:165], v[166:169], v[200:203], v[2:5]
	s_setprio 2
	s_barrier
	ds_read_b128 v[166:169], v226
	ds_read_b128 v[192:195], v226 offset:1024
	ds_read_b128 v[196:199], v226 offset:2048
	ds_read_b128 v[200:203], v226 offset:3072
	ds_read_b128 v[238:241], v227
	ds_read_b128 v[242:245], v227 offset:1024
	ds_read_b128 v[246:249], v227 offset:2048
	ds_read_b128 v[226:229], v227 offset:3072
	s_add_u32 s14, s72, 0x100000
	s_addc_u32 s15, s73, 0
	s_mov_b32 m0, s48
	v_lshl_add_u64 v[2:3], s[14:15], 0, v[136:137]
	ds_read_b128 v[6:9], v209 offset:32768
	ds_read_b128 v[10:13], v209 offset:33792
	ds_read_b128 v[14:17], v209 offset:34816
	ds_read_b128 v[18:21], v209 offset:35840
	ds_read_b128 v[22:25], v209 offset:36864
	ds_read_b128 v[26:29], v209 offset:37888
	ds_read_b128 v[30:33], v209 offset:38912
	ds_read_b128 v[102:105], v209 offset:39936
	global_load_lds_dwordx4 v[2:3], off
	v_lshl_add_u64 v[2:3], s[14:15], 0, v[132:133]
	s_mov_b32 m0, s52
	s_nop 0
	global_load_lds_dwordx4 v[2:3], off
	s_waitcnt vmcnt(8)
	s_waitcnt lgkmcnt(0)
	s_barrier
	s_setprio 1
	s_waitcnt lgkmcnt(0)
	v_mfma_f32_16x16x32_bf16 v[2:5], v[166:169], v[6:9], v[66:69]
	v_mfma_f32_16x16x32_bf16 v[126:129], v[192:195], v[10:13], v[2:5]
	v_mfma_f32_16x16x32_bf16 v[2:5], v[196:199], v[6:9], v[70:73]
	v_mfma_f32_16x16x32_bf16 v[122:125], v[200:203], v[10:13], v[2:5]
	v_mfma_f32_16x16x32_bf16 v[2:5], v[166:169], v[14:17], v[74:77]
	v_mfma_f32_16x16x32_bf16 v[118:121], v[192:195], v[18:21], v[2:5]
	v_mfma_f32_16x16x32_bf16 v[2:5], v[196:199], v[14:17], v[78:81]
	v_mfma_f32_16x16x32_bf16 v[114:117], v[200:203], v[18:21], v[2:5]
	v_mfma_f32_16x16x32_bf16 v[2:5], v[166:169], v[22:25], v[82:85]
	v_mfma_f32_16x16x32_bf16 v[110:113], v[192:195], v[26:29], v[2:5]
	v_mfma_f32_16x16x32_bf16 v[2:5], v[196:199], v[22:25], v[86:89]
	v_mfma_f32_16x16x32_bf16 v[106:109], v[200:203], v[26:29], v[2:5]
	v_mfma_f32_16x16x32_bf16 v[2:5], v[166:169], v[30:33], v[90:93]
	v_mfma_f32_16x16x32_bf16 v[94:97], v[192:195], v[102:105], v[2:5]
	v_mfma_f32_16x16x32_bf16 v[2:5], v[196:199], v[30:33], v[214:217]
	v_mfma_f32_16x16x32_bf16 v[90:93], v[200:203], v[102:105], v[2:5]
	s_setprio 0
	s_setprio 1
	v_mfma_f32_16x16x32_bf16 v[2:5], v[238:241], v[6:9], v[98:101]
	v_mfma_f32_16x16x32_bf16 v[6:9], v[246:249], v[6:9], v[34:37]
	v_mfma_f32_16x16x32_bf16 v[2:5], v[242:245], v[10:13], v[2:5]
	v_mfma_f32_16x16x32_bf16 v[6:9], v[226:229], v[10:13], v[6:9]
	v_mfma_f32_16x16x32_bf16 v[10:13], v[238:241], v[14:17], v[38:41]
	v_mfma_f32_16x16x32_bf16 v[14:17], v[246:249], v[14:17], v[42:45]
	v_mfma_f32_16x16x32_bf16 v[10:13], v[242:245], v[18:21], v[10:13]
	v_mfma_f32_16x16x32_bf16 v[14:17], v[226:229], v[18:21], v[14:17]
	v_mfma_f32_16x16x32_bf16 v[18:21], v[238:241], v[22:25], v[46:49]
	v_mfma_f32_16x16x32_bf16 v[22:25], v[246:249], v[22:25], v[50:53]
	v_mfma_f32_16x16x32_bf16 v[18:21], v[242:245], v[26:29], v[18:21]
	v_mfma_f32_16x16x32_bf16 v[22:25], v[226:229], v[26:29], v[22:25]
	v_mfma_f32_16x16x32_bf16 v[26:29], v[238:241], v[30:33], v[54:57]
	v_mfma_f32_16x16x32_bf16 v[30:33], v[246:249], v[30:33], v[58:61]
	v_mfma_f32_16x16x32_bf16 v[26:29], v[242:245], v[102:105], v[26:29]
	v_mfma_f32_16x16x32_bf16 v[30:33], v[226:229], v[102:105], v[30:33]
	s_setprio 2
	s_barrier
	s_mov_b32 m0, s10
	v_lshl_add_u64 v[34:35], v[178:179], 0, s[94:95]
	s_add_u32 s10, s70, 0x10080
	ds_read_b128 v[38:41], v209 offset:49152
	ds_read_b128 v[42:45], v209 offset:50176
	ds_read_b128 v[46:49], v209 offset:51200
	ds_read_b128 v[50:53], v209 offset:52224
	ds_read_b128 v[54:57], v209 offset:53248
	ds_read_b128 v[58:61], v209 offset:54272
	ds_read_b128 v[214:217], v209 offset:55296
	ds_read_b128 v[174:177], v209 offset:56320
	global_load_lds_dwordx4 v[34:35], off
	v_lshl_add_u64 v[34:35], v[204:205], 0, s[94:95]
	s_mov_b32 m0, s64
	s_addc_u32 s11, s71, 0
	global_load_lds_dwordx4 v[34:35], off
	v_lshl_add_u64 v[34:35], s[10:11], 0, v[134:135]
	s_mov_b32 m0, s16
	s_nop 0
	global_load_lds_dwordx4 v[34:35], off
	v_lshl_add_u64 v[34:35], s[10:11], 0, v[130:131]
	s_mov_b32 m0, s17
	s_nop 0
	global_load_lds_dwordx4 v[34:35], off
	v_lshl_add_u64 v[34:35], v[230:231], 0, s[94:95]
	s_mov_b32 m0, s74
	s_nop 0
	global_load_lds_dwordx4 v[34:35], off
	v_lshl_add_u64 v[34:35], v[234:235], 0, s[94:95]
	s_mov_b32 m0, s75
	s_nop 0
	global_load_lds_dwordx4 v[34:35], off
	s_waitcnt vmcnt(8)
	s_waitcnt lgkmcnt(0)
	s_barrier
	s_setprio 1
	s_waitcnt lgkmcnt(0)
	v_mfma_f32_16x16x32_bf16 v[34:37], v[166:169], v[38:41], v[138:141]
	v_mfma_f32_16x16x32_bf16 v[102:105], v[192:195], v[42:45], v[34:37]
	v_mfma_f32_16x16x32_bf16 v[34:37], v[196:199], v[38:41], v[142:145]
	v_mfma_f32_16x16x32_bf16 v[98:101], v[200:203], v[42:45], v[34:37]
	v_mfma_f32_16x16x32_bf16 v[34:37], v[166:169], v[46:49], v[146:149]
	v_mfma_f32_16x16x32_bf16 v[86:89], v[192:195], v[50:53], v[34:37]
	v_mfma_f32_16x16x32_bf16 v[34:37], v[196:199], v[46:49], v[150:153]
	v_mfma_f32_16x16x32_bf16 v[82:85], v[200:203], v[50:53], v[34:37]
	v_mfma_f32_16x16x32_bf16 v[34:37], v[166:169], v[54:57], v[154:157]
	v_mfma_f32_16x16x32_bf16 v[78:81], v[192:195], v[58:61], v[34:37]
	v_mfma_f32_16x16x32_bf16 v[34:37], v[196:199], v[54:57], v[158:161]
	v_mfma_f32_16x16x32_bf16 v[74:77], v[200:203], v[58:61], v[34:37]
	v_mfma_f32_16x16x32_bf16 v[34:37], v[166:169], v[214:217], v[210:213]
	v_mfma_f32_16x16x32_bf16 v[70:73], v[192:195], v[174:177], v[34:37]
	v_mfma_f32_16x16x32_bf16 v[34:37], v[196:199], v[214:217], v[218:221]
	v_mfma_f32_16x16x32_bf16 v[66:69], v[200:203], v[174:177], v[34:37]
	s_setprio 0
	s_setprio 1
	v_mfma_f32_16x16x32_bf16 v[34:37], v[238:241], v[38:41], v[222:225]
	v_mfma_f32_16x16x32_bf16 v[38:41], v[246:249], v[38:41], v[170:173]
	v_mfma_f32_16x16x32_bf16 v[34:37], v[242:245], v[42:45], v[34:37]
	v_mfma_f32_16x16x32_bf16 v[38:41], v[226:229], v[42:45], v[38:41]
	v_mfma_f32_16x16x32_bf16 v[42:45], v[238:241], v[46:49], v[250:253]
	v_mfma_f32_16x16x32_bf16 v[46:49], v[246:249], v[46:49], v[180:183]
	v_mfma_f32_16x16x32_bf16 v[42:45], v[242:245], v[50:53], v[42:45]
	v_mfma_f32_16x16x32_bf16 v[46:49], v[226:229], v[50:53], v[46:49]
	v_mfma_f32_16x16x32_bf16 v[50:53], v[238:241], v[54:57], v[62:65]
	v_mfma_f32_16x16x32_bf16 v[54:57], v[246:249], v[54:57], v[184:187]
	v_mfma_f32_16x16x32_bf16 v[50:53], v[242:245], v[58:61], v[50:53]
	v_mfma_f32_16x16x32_bf16 v[54:57], v[226:229], v[58:61], v[54:57]
	v_mfma_f32_16x16x32_bf16 v[58:61], v[238:241], v[214:217], v[188:191]
	v_mfma_f32_16x16x32_bf16 v[62:65], v[246:249], v[214:217], v[162:165]
	v_mfma_f32_16x16x32_bf16 v[58:61], v[242:245], v[174:177], v[58:61]
	v_mfma_f32_16x16x32_bf16 v[62:65], v[226:229], v[174:177], v[62:65]
	s_setprio 2
	s_barrier
	s_andn2_b64 vcc, exec, s[38:39]
	s_cbranch_vccnz .LBB0_362
	s_barrier

.LBB0_685:
	s_add_u32 s36, s12, s38
	s_addc_u32 s42, s13, s39
	s_add_u32 s36, s36, 0x100
	s_addc_u32 s42, s42, 0
	s_add_u32 s62, s35, s38
	s_addc_u32 s43, s63, s39
	s_cmpk_eq_i32 s38, 0xf00
	s_cselect_b32 s45, s27, s42
	s_cselect_b32 s44, s60, s36
	s_cselect_b32 s43, s21, s43
	s_cselect_b32 s42, s61, s62
	s_add_i32 s36, 0, 0x10000
	v_add_u32_e32 v0, s36, v188
	s_add_i32 s62, 0, 0x14000
	ds_read_b128 v[138:141], v0
	ds_read_b128 v[142:145], v0 offset:1024
	ds_read_b128 v[146:149], v0 offset:2048
	ds_read_b128 v[150:153], v0 offset:3072
	v_add_u32_e32 v0, s62, v188
	ds_read_b128 v[170:173], v0
	ds_read_b128 v[174:177], v0 offset:1024
	ds_read_b128 v[178:181], v0 offset:2048
	ds_read_b128 v[182:185], v0 offset:3072
	v_lshl_add_u64 v[2:3], v[136:137], 0, s[38:39]
	s_add_i32 m0, s33, 0xc000
	ds_read_b128 v[190:193], v189
	ds_read_b128 v[194:197], v189 offset:1024
	ds_read_b128 v[198:201], v189 offset:2048
	ds_read_b128 v[202:205], v189 offset:3072
	ds_read_b128 v[206:209], v189 offset:4096
	ds_read_b128 v[210:213], v189 offset:5120
	ds_read_b128 v[214:217], v189 offset:6144
	ds_read_b128 v[218:221], v189 offset:7168
	global_load_lds_dwordx4 v[2:3], off
	v_lshl_add_u64 v[2:3], v[134:135], 0, s[38:39]
	s_add_i32 m0, s33, 0xe000
	s_nop 0
	global_load_lds_dwordx4 v[2:3], off
	s_waitcnt vmcnt(8)
	s_waitcnt lgkmcnt(0)
	s_barrier
	s_setprio 1
	s_waitcnt lgkmcnt(0)
	v_mfma_f32_16x16x32_bf16 v[128:131], v[138:141], v[190:193], v[128:131]
	v_mfma_f32_16x16x32_bf16 v[124:127], v[146:149], v[190:193], v[124:127]
	v_mfma_f32_16x16x32_bf16 v[112:115], v[138:141], v[198:201], v[112:115]
	v_mfma_f32_16x16x32_bf16 v[108:111], v[146:149], v[198:201], v[108:111]
	v_mfma_f32_16x16x32_bf16 v[96:99], v[138:141], v[206:209], v[96:99]
	v_mfma_f32_16x16x32_bf16 v[92:95], v[146:149], v[206:209], v[92:95]
	v_mfma_f32_16x16x32_bf16 v[80:83], v[138:141], v[214:217], v[80:83]
	v_mfma_f32_16x16x32_bf16 v[76:79], v[146:149], v[214:217], v[76:79]
	v_mfma_f32_16x16x32_bf16 v[128:131], v[142:145], v[194:197], v[128:131]
	v_mfma_f32_16x16x32_bf16 v[124:127], v[150:153], v[194:197], v[124:127]
	v_mfma_f32_16x16x32_bf16 v[112:115], v[142:145], v[202:205], v[112:115]
	v_mfma_f32_16x16x32_bf16 v[108:111], v[150:153], v[202:205], v[108:111]
	v_mfma_f32_16x16x32_bf16 v[96:99], v[142:145], v[210:213], v[96:99]
	v_mfma_f32_16x16x32_bf16 v[92:95], v[150:153], v[210:213], v[92:95]
	v_mfma_f32_16x16x32_bf16 v[80:83], v[142:145], v[218:221], v[80:83]
	v_mfma_f32_16x16x32_bf16 v[76:79], v[150:153], v[218:221], v[76:79]
	s_setprio 0
	s_setprio 1
	v_mfma_f32_16x16x32_bf16 v[120:123], v[170:173], v[190:193], v[120:123]
	v_mfma_f32_16x16x32_bf16 v[116:119], v[178:181], v[190:193], v[116:119]
	v_mfma_f32_16x16x32_bf16 v[104:107], v[170:173], v[198:201], v[104:107]
	v_mfma_f32_16x16x32_bf16 v[100:103], v[178:181], v[198:201], v[100:103]
	v_mfma_f32_16x16x32_bf16 v[88:91], v[170:173], v[206:209], v[88:91]
	v_mfma_f32_16x16x32_bf16 v[84:87], v[178:181], v[206:209], v[84:87]
	v_mfma_f32_16x16x32_bf16 v[72:75], v[170:173], v[214:217], v[72:75]
	v_mfma_f32_16x16x32_bf16 v[68:71], v[178:181], v[214:217], v[68:71]
	v_mfma_f32_16x16x32_bf16 v[120:123], v[174:177], v[194:197], v[120:123]
	v_mfma_f32_16x16x32_bf16 v[116:119], v[182:185], v[194:197], v[116:119]
	v_mfma_f32_16x16x32_bf16 v[104:107], v[174:177], v[202:205], v[104:107]
	v_mfma_f32_16x16x32_bf16 v[100:103], v[182:185], v[202:205], v[100:103]
	v_mfma_f32_16x16x32_bf16 v[88:91], v[174:177], v[210:213], v[88:91]
	v_mfma_f32_16x16x32_bf16 v[84:87], v[182:185], v[210:213], v[84:87]
	v_mfma_f32_16x16x32_bf16 v[72:75], v[174:177], v[218:221], v[72:75]
	v_mfma_f32_16x16x32_bf16 v[68:71], v[182:185], v[218:221], v[68:71]
	s_setprio 2
	s_barrier
	s_add_i32 s36, s36, s41
	v_lshl_add_u64 v[154:155], s[42:43], 0, v[160:161]
	s_mov_b32 m0, s36
	ds_read_b128 v[190:193], v189 offset:16384
	ds_read_b128 v[194:197], v189 offset:17408
	ds_read_b128 v[198:201], v189 offset:18432
	ds_read_b128 v[202:205], v189 offset:19456
	ds_read_b128 v[206:209], v189 offset:20480
	ds_read_b128 v[210:213], v189 offset:21504
	ds_read_b128 v[214:217], v189 offset:22528
	ds_read_b128 v[218:221], v189 offset:23552
	global_load_lds_dwordx4 v[154:155], off
	s_add_i32 m0, s36, 0x2000
	s_add_u32 s66, s42, 0x80000
	v_lshl_add_u64 v[222:223], s[42:43], 0, v[156:157]
	s_addc_u32 s67, s43, 0
	s_add_i32 s36, s62, s41
	global_load_lds_dwordx4 v[222:223], off
	v_lshl_add_u64 v[2:3], s[66:67], 0, v[160:161]
	s_mov_b32 m0, s36
	v_lshl_add_u64 v[224:225], s[44:45], 0, v[162:163]
	global_load_lds_dwordx4 v[2:3], off
	v_lshl_add_u64 v[2:3], s[66:67], 0, v[156:157]
	s_add_i32 m0, s36, 0x2000
	v_lshl_add_u64 v[226:227], s[44:45], 0, v[158:159]
	global_load_lds_dwordx4 v[2:3], off
	s_mov_b32 m0, s33
	s_nop 0
	global_load_lds_dwordx4 v[224:225], off
	s_mov_b32 m0, s56
	s_nop 0
	global_load_lds_dwordx4 v[226:227], off
	s_waitcnt vmcnt(8)
	s_waitcnt lgkmcnt(0)
	s_barrier
	s_setprio 1
	s_waitcnt lgkmcnt(0)
	v_mfma_f32_16x16x32_bf16 v[64:67], v[138:141], v[190:193], v[64:67]
	v_mfma_f32_16x16x32_bf16 v[60:63], v[146:149], v[190:193], v[60:63]
	v_mfma_f32_16x16x32_bf16 v[48:51], v[138:141], v[198:201], v[48:51]
	v_mfma_f32_16x16x32_bf16 v[44:47], v[146:149], v[198:201], v[44:47]
	v_mfma_f32_16x16x32_bf16 v[32:35], v[138:141], v[206:209], v[32:35]
	v_mfma_f32_16x16x32_bf16 v[28:31], v[146:149], v[206:209], v[28:31]
	v_mfma_f32_16x16x32_bf16 v[16:19], v[138:141], v[214:217], v[16:19]
	v_mfma_f32_16x16x32_bf16 v[12:15], v[146:149], v[214:217], v[12:15]
	v_mfma_f32_16x16x32_bf16 v[64:67], v[142:145], v[194:197], v[64:67]
	v_mfma_f32_16x16x32_bf16 v[60:63], v[150:153], v[194:197], v[60:63]
	v_mfma_f32_16x16x32_bf16 v[48:51], v[142:145], v[202:205], v[48:51]
	v_mfma_f32_16x16x32_bf16 v[44:47], v[150:153], v[202:205], v[44:47]
	v_mfma_f32_16x16x32_bf16 v[32:35], v[142:145], v[210:213], v[32:35]
	v_mfma_f32_16x16x32_bf16 v[28:31], v[150:153], v[210:213], v[28:31]
	v_mfma_f32_16x16x32_bf16 v[16:19], v[142:145], v[218:221], v[16:19]
	v_mfma_f32_16x16x32_bf16 v[12:15], v[150:153], v[218:221], v[12:15]
	s_setprio 0
	s_setprio 1
	v_mfma_f32_16x16x32_bf16 v[56:59], v[170:173], v[190:193], v[56:59]
	v_mfma_f32_16x16x32_bf16 v[52:55], v[178:181], v[190:193], v[52:55]
	v_mfma_f32_16x16x32_bf16 v[40:43], v[170:173], v[198:201], v[40:43]
	v_mfma_f32_16x16x32_bf16 v[36:39], v[178:181], v[198:201], v[36:39]
	v_mfma_f32_16x16x32_bf16 v[24:27], v[170:173], v[206:209], v[24:27]
	v_mfma_f32_16x16x32_bf16 v[20:23], v[178:181], v[206:209], v[20:23]
	v_mfma_f32_16x16x32_bf16 v[8:11], v[170:173], v[214:217], v[8:11]
	v_mfma_f32_16x16x32_bf16 v[2:5], v[178:181], v[214:217], v[4:7]
	v_mfma_f32_16x16x32_bf16 v[56:59], v[174:177], v[194:197], v[56:59]
	v_mfma_f32_16x16x32_bf16 v[52:55], v[182:185], v[194:197], v[52:55]
	v_mfma_f32_16x16x32_bf16 v[40:43], v[174:177], v[202:205], v[40:43]
	v_mfma_f32_16x16x32_bf16 v[36:39], v[182:185], v[202:205], v[36:39]
	v_mfma_f32_16x16x32_bf16 v[24:27], v[174:177], v[210:213], v[24:27]
	v_mfma_f32_16x16x32_bf16 v[20:23], v[182:185], v[210:213], v[20:23]
	v_mfma_f32_16x16x32_bf16 v[8:11], v[174:177], v[218:221], v[8:11]
	v_mfma_f32_16x16x32_bf16 v[2:5], v[182:185], v[218:221], v[2:5]
	s_setprio 2
	s_barrier
	s_add_i32 s36, 0, 0x18000
	v_add_u32_e32 v0, s36, v188
	s_add_i32 s62, 0, 0x1c000
	ds_read_b128 v[138:141], v0
	ds_read_b128 v[142:145], v0 offset:1024
	ds_read_b128 v[146:149], v0 offset:2048
	ds_read_b128 v[150:153], v0 offset:3072
	v_add_u32_e32 v0, s62, v188
	ds_read_b128 v[170:173], v0
	ds_read_b128 v[174:177], v0 offset:1024
	ds_read_b128 v[178:181], v0 offset:2048
	ds_read_b128 v[182:185], v0 offset:3072
	s_add_u32 s44, s44, 0x80000
	s_addc_u32 s45, s45, 0
	s_mov_b32 m0, s57
	v_lshl_add_u64 v[6:7], s[44:45], 0, v[162:163]
	ds_read_b128 v[190:193], v189 offset:32768
	ds_read_b128 v[194:197], v189 offset:33792
	ds_read_b128 v[198:201], v189 offset:34816
	ds_read_b128 v[202:205], v189 offset:35840
	ds_read_b128 v[206:209], v189 offset:36864
	ds_read_b128 v[210:213], v189 offset:37888
	ds_read_b128 v[214:217], v189 offset:38912
	ds_read_b128 v[218:221], v189 offset:39936
	global_load_lds_dwordx4 v[6:7], off
	v_lshl_add_u64 v[6:7], s[44:45], 0, v[158:159]
	s_mov_b32 m0, s59
	s_nop 0
	global_load_lds_dwordx4 v[6:7], off
	s_waitcnt vmcnt(8)
	s_waitcnt lgkmcnt(0)
	s_barrier
	s_setprio 1
	s_waitcnt lgkmcnt(0)
	v_mfma_f32_16x16x32_bf16 v[128:131], v[138:141], v[190:193], v[128:131]
	v_mfma_f32_16x16x32_bf16 v[124:127], v[146:149], v[190:193], v[124:127]
	v_mfma_f32_16x16x32_bf16 v[112:115], v[138:141], v[198:201], v[112:115]
	v_mfma_f32_16x16x32_bf16 v[108:111], v[146:149], v[198:201], v[108:111]
	v_mfma_f32_16x16x32_bf16 v[96:99], v[138:141], v[206:209], v[96:99]
	v_mfma_f32_16x16x32_bf16 v[92:95], v[146:149], v[206:209], v[92:95]
	v_mfma_f32_16x16x32_bf16 v[80:83], v[138:141], v[214:217], v[80:83]
	v_mfma_f32_16x16x32_bf16 v[76:79], v[146:149], v[214:217], v[76:79]
	v_mfma_f32_16x16x32_bf16 v[128:131], v[142:145], v[194:197], v[128:131]
	v_mfma_f32_16x16x32_bf16 v[124:127], v[150:153], v[194:197], v[124:127]
	v_mfma_f32_16x16x32_bf16 v[112:115], v[142:145], v[202:205], v[112:115]
	v_mfma_f32_16x16x32_bf16 v[108:111], v[150:153], v[202:205], v[108:111]
	v_mfma_f32_16x16x32_bf16 v[96:99], v[142:145], v[210:213], v[96:99]
	v_mfma_f32_16x16x32_bf16 v[92:95], v[150:153], v[210:213], v[92:95]
	v_mfma_f32_16x16x32_bf16 v[80:83], v[142:145], v[218:221], v[80:83]
	v_mfma_f32_16x16x32_bf16 v[76:79], v[150:153], v[218:221], v[76:79]
	s_setprio 0
	s_setprio 1
	v_mfma_f32_16x16x32_bf16 v[120:123], v[170:173], v[190:193], v[120:123]
	v_mfma_f32_16x16x32_bf16 v[116:119], v[178:181], v[190:193], v[116:119]
	v_mfma_f32_16x16x32_bf16 v[104:107], v[170:173], v[198:201], v[104:107]
	v_mfma_f32_16x16x32_bf16 v[100:103], v[178:181], v[198:201], v[100:103]
	v_mfma_f32_16x16x32_bf16 v[88:91], v[170:173], v[206:209], v[88:91]
	v_mfma_f32_16x16x32_bf16 v[84:87], v[178:181], v[206:209], v[84:87]
	v_mfma_f32_16x16x32_bf16 v[72:75], v[170:173], v[214:217], v[72:75]
	v_mfma_f32_16x16x32_bf16 v[68:71], v[178:181], v[214:217], v[68:71]
	v_mfma_f32_16x16x32_bf16 v[120:123], v[174:177], v[194:197], v[120:123]
	v_mfma_f32_16x16x32_bf16 v[116:119], v[182:185], v[194:197], v[116:119]
	v_mfma_f32_16x16x32_bf16 v[104:107], v[174:177], v[202:205], v[104:107]
	v_mfma_f32_16x16x32_bf16 v[100:103], v[182:185], v[202:205], v[100:103]
	v_mfma_f32_16x16x32_bf16 v[88:91], v[174:177], v[210:213], v[88:91]
	v_mfma_f32_16x16x32_bf16 v[84:87], v[182:185], v[210:213], v[84:87]
	v_mfma_f32_16x16x32_bf16 v[72:75], v[174:177], v[218:221], v[72:75]
	v_mfma_f32_16x16x32_bf16 v[68:71], v[182:185], v[218:221], v[68:71]
	s_setprio 2
	s_barrier
	s_add_i32 s36, s36, s41
	v_lshl_add_u64 v[6:7], v[154:155], 0, s[94:95]
	s_mov_b32 m0, s36
	ds_read_b128 v[190:193], v189 offset:49152
	ds_read_b128 v[194:197], v189 offset:50176
	ds_read_b128 v[198:201], v189 offset:51200
	ds_read_b128 v[202:205], v189 offset:52224
	ds_read_b128 v[206:209], v189 offset:53248
	ds_read_b128 v[210:213], v189 offset:54272
	ds_read_b128 v[214:217], v189 offset:55296
	ds_read_b128 v[218:221], v189 offset:56320
	global_load_lds_dwordx4 v[6:7], off
	s_add_i32 m0, s36, 0x2000
	s_add_u32 s42, s42, 0x80080
	v_lshl_add_u64 v[6:7], v[222:223], 0, s[94:95]
	s_addc_u32 s43, s43, 0
	s_add_i32 s36, s62, s41
	global_load_lds_dwordx4 v[6:7], off
	v_lshl_add_u64 v[6:7], s[42:43], 0, v[160:161]
	s_mov_b32 m0, s36
	s_nop 0
	global_load_lds_dwordx4 v[6:7], off
	v_lshl_add_u64 v[6:7], s[42:43], 0, v[156:157]
	s_add_i32 m0, s36, 0x2000
	s_nop 0
	global_load_lds_dwordx4 v[6:7], off
	v_lshl_add_u64 v[6:7], v[224:225], 0, s[94:95]
	s_mov_b32 m0, s48
	s_nop 0
	global_load_lds_dwordx4 v[6:7], off
	v_lshl_add_u64 v[6:7], v[226:227], 0, s[94:95]
	s_mov_b32 m0, s52
	s_nop 0
	global_load_lds_dwordx4 v[6:7], off
	s_waitcnt vmcnt(8)
	s_waitcnt lgkmcnt(0)
	s_barrier
	s_setprio 1
	s_waitcnt lgkmcnt(0)
	v_mfma_f32_16x16x32_bf16 v[64:67], v[138:141], v[190:193], v[64:67]
	v_mfma_f32_16x16x32_bf16 v[60:63], v[146:149], v[190:193], v[60:63]
	v_mfma_f32_16x16x32_bf16 v[48:51], v[138:141], v[198:201], v[48:51]
	v_mfma_f32_16x16x32_bf16 v[44:47], v[146:149], v[198:201], v[44:47]
	v_mfma_f32_16x16x32_bf16 v[32:35], v[138:141], v[206:209], v[32:35]
	v_mfma_f32_16x16x32_bf16 v[28:31], v[146:149], v[206:209], v[28:31]
	v_mfma_f32_16x16x32_bf16 v[16:19], v[138:141], v[214:217], v[16:19]
	v_mfma_f32_16x16x32_bf16 v[12:15], v[146:149], v[214:217], v[12:15]
	v_mfma_f32_16x16x32_bf16 v[64:67], v[142:145], v[194:197], v[64:67]
	v_mfma_f32_16x16x32_bf16 v[60:63], v[150:153], v[194:197], v[60:63]
	v_mfma_f32_16x16x32_bf16 v[48:51], v[142:145], v[202:205], v[48:51]
	v_mfma_f32_16x16x32_bf16 v[44:47], v[150:153], v[202:205], v[44:47]
	v_mfma_f32_16x16x32_bf16 v[32:35], v[142:145], v[210:213], v[32:35]
	v_mfma_f32_16x16x32_bf16 v[28:31], v[150:153], v[210:213], v[28:31]
	v_mfma_f32_16x16x32_bf16 v[16:19], v[142:145], v[218:221], v[16:19]
	v_mfma_f32_16x16x32_bf16 v[12:15], v[150:153], v[218:221], v[12:15]
	s_setprio 0
	s_setprio 1
	v_mfma_f32_16x16x32_bf16 v[56:59], v[170:173], v[190:193], v[56:59]
	v_mfma_f32_16x16x32_bf16 v[52:55], v[178:181], v[190:193], v[52:55]
	v_mfma_f32_16x16x32_bf16 v[40:43], v[170:173], v[198:201], v[40:43]
	v_mfma_f32_16x16x32_bf16 v[36:39], v[178:181], v[198:201], v[36:39]
	v_mfma_f32_16x16x32_bf16 v[24:27], v[170:173], v[206:209], v[24:27]
	v_mfma_f32_16x16x32_bf16 v[20:23], v[178:181], v[206:209], v[20:23]
	v_mfma_f32_16x16x32_bf16 v[6:9], v[170:173], v[214:217], v[8:11]
	v_mfma_f32_16x16x32_bf16 v[2:5], v[178:181], v[214:217], v[2:5]
	v_mfma_f32_16x16x32_bf16 v[56:59], v[174:177], v[194:197], v[56:59]
	v_mfma_f32_16x16x32_bf16 v[52:55], v[182:185], v[194:197], v[52:55]
	v_mfma_f32_16x16x32_bf16 v[40:43], v[174:177], v[202:205], v[40:43]
	v_mfma_f32_16x16x32_bf16 v[36:39], v[182:185], v[202:205], v[36:39]
	v_mfma_f32_16x16x32_bf16 v[24:27], v[174:177], v[210:213], v[24:27]
	v_mfma_f32_16x16x32_bf16 v[20:23], v[182:185], v[210:213], v[20:23]
	v_mfma_f32_16x16x32_bf16 v[8:11], v[174:177], v[218:221], v[6:9]
	v_mfma_f32_16x16x32_bf16 v[4:7], v[182:185], v[218:221], v[2:5]
	s_setprio 2
	s_barrier
	s_add_i32 s64, s64, 2
	s_add_u32 s38, s38, 0x100
	s_addc_u32 s39, s39, 0
	s_cmp_gt_u32 s64, 29
	s_cbranch_scc1 .LBB0_688

.LBB0_773:
	s_add_u32 s6, s12, 0xfff80080
	s_addc_u32 s7, s13, -1
	s_add_i32 s19, 0, 0x10000
	s_cmp_eq_u32 s18, 28
	s_cselect_b32 s15, s61, s7
	s_cselect_b32 s14, vcc_lo, s6
	s_cselect_b32 s7, s35, s17
	s_cselect_b32 s6, vcc_hi, s16
	s_add_i32 s80, 0, 0x14000
	v_add_u32_e32 v142, s19, v208
	v_add_u32_e32 v158, s80, v208
	ds_read_b128 v[130:133], v142
	ds_read_b128 v[134:137], v142 offset:1024
	ds_read_b128 v[138:141], v142 offset:2048
	ds_read_b128 v[142:145], v142 offset:3072
	ds_read_b128 v[146:149], v158
	ds_read_b128 v[150:153], v158 offset:1024
	ds_read_b128 v[154:157], v158 offset:2048
	ds_read_b128 v[158:161], v158 offset:3072
	v_lshl_add_u64 v[170:171], s[12:13], 0, v[184:185]
	s_add_i32 m0, s33, 0xc000
	ds_read_b128 v[162:165], v209
	ds_read_b128 v[166:169], v209 offset:1024
	ds_read_b128 v[176:179], v209 offset:2048
	ds_read_b128 v[186:189], v209 offset:3072
	ds_read_b128 v[190:193], v209 offset:4096
	ds_read_b128 v[194:197], v209 offset:5120
	ds_read_b128 v[198:201], v209 offset:6144
	ds_read_b128 v[202:205], v209 offset:7168
	global_load_lds_dwordx4 v[170:171], off
	v_lshl_add_u64 v[170:171], s[12:13], 0, v[182:183]
	s_add_i32 m0, s33, 0xe000
	s_nop 0
	global_load_lds_dwordx4 v[170:171], off
	s_waitcnt vmcnt(8)
	s_waitcnt lgkmcnt(0)
	s_barrier
	s_setprio 1
	s_waitcnt lgkmcnt(0)
	v_mfma_f32_16x16x32_bf16 v[122:125], v[130:133], v[162:165], v[122:125]
	v_mfma_f32_16x16x32_bf16 v[90:93], v[138:141], v[162:165], v[90:93]
	v_mfma_f32_16x16x32_bf16 v[110:113], v[130:133], v[176:179], v[110:113]
	v_mfma_f32_16x16x32_bf16 v[46:49], v[138:141], v[176:179], v[46:49]
	v_mfma_f32_16x16x32_bf16 v[106:109], v[130:133], v[190:193], v[106:109]
	v_mfma_f32_16x16x32_bf16 v[42:45], v[138:141], v[190:193], v[42:45]
	v_mfma_f32_16x16x32_bf16 v[126:129], v[130:133], v[198:201], v[126:129]
	v_mfma_f32_16x16x32_bf16 v[54:57], v[138:141], v[198:201], v[54:57]
	v_mfma_f32_16x16x32_bf16 v[122:125], v[134:137], v[166:169], v[122:125]
	v_mfma_f32_16x16x32_bf16 v[90:93], v[142:145], v[166:169], v[90:93]
	v_mfma_f32_16x16x32_bf16 v[110:113], v[134:137], v[186:189], v[110:113]
	v_mfma_f32_16x16x32_bf16 v[46:49], v[142:145], v[186:189], v[46:49]
	v_mfma_f32_16x16x32_bf16 v[106:109], v[134:137], v[194:197], v[106:109]
	v_mfma_f32_16x16x32_bf16 v[42:45], v[142:145], v[194:197], v[42:45]
	v_mfma_f32_16x16x32_bf16 v[126:129], v[134:137], v[202:205], v[126:129]
	v_mfma_f32_16x16x32_bf16 v[54:57], v[142:145], v[202:205], v[54:57]
	s_setprio 0
	s_setprio 1
	v_mfma_f32_16x16x32_bf16 v[114:117], v[146:149], v[162:165], v[114:117]
	v_mfma_f32_16x16x32_bf16 v[94:97], v[154:157], v[162:165], v[94:97]
	v_mfma_f32_16x16x32_bf16 v[102:105], v[146:149], v[176:179], v[102:105]
	v_mfma_f32_16x16x32_bf16 v[38:41], v[154:157], v[176:179], v[38:41]
	v_mfma_f32_16x16x32_bf16 v[98:101], v[146:149], v[190:193], v[98:101]
	v_mfma_f32_16x16x32_bf16 v[34:37], v[154:157], v[190:193], v[34:37]
	v_mfma_f32_16x16x32_bf16 v[118:121], v[146:149], v[198:201], v[118:121]
	v_mfma_f32_16x16x32_bf16 v[50:53], v[154:157], v[198:201], v[50:53]
	v_mfma_f32_16x16x32_bf16 v[114:117], v[150:153], v[166:169], v[114:117]
	v_mfma_f32_16x16x32_bf16 v[94:97], v[158:161], v[166:169], v[94:97]
	v_mfma_f32_16x16x32_bf16 v[102:105], v[150:153], v[186:189], v[102:105]
	v_mfma_f32_16x16x32_bf16 v[38:41], v[158:161], v[186:189], v[38:41]
	v_mfma_f32_16x16x32_bf16 v[98:101], v[150:153], v[194:197], v[98:101]
	v_mfma_f32_16x16x32_bf16 v[34:37], v[158:161], v[194:197], v[34:37]
	v_mfma_f32_16x16x32_bf16 v[118:121], v[150:153], v[202:205], v[118:121]
	v_mfma_f32_16x16x32_bf16 v[50:53], v[158:161], v[202:205], v[50:53]
	s_setprio 2
	s_barrier
	s_add_i32 s19, s19, s41
	v_lshl_add_u64 v[170:171], s[6:7], 0, v[0:1]
	s_mov_b32 m0, s19
	ds_read_b128 v[162:165], v209 offset:16384
	ds_read_b128 v[166:169], v209 offset:17408
	ds_read_b128 v[176:179], v209 offset:18432
	ds_read_b128 v[186:189], v209 offset:19456
	ds_read_b128 v[190:193], v209 offset:20480
	ds_read_b128 v[194:197], v209 offset:21504
	ds_read_b128 v[198:201], v209 offset:22528
	ds_read_b128 v[202:205], v209 offset:23552
	global_load_lds_dwordx4 v[170:171], off
	s_add_i32 m0, s19, 0x2000
	s_add_u32 s24, s6, 0x80000
	v_lshl_add_u64 v[210:211], s[6:7], 0, v[172:173]
	s_addc_u32 s25, s7, 0
	s_add_i32 s19, s80, s41
	global_load_lds_dwordx4 v[210:211], off
	v_lshl_add_u64 v[212:213], s[24:25], 0, v[0:1]
	s_mov_b32 m0, s19
	v_lshl_add_u64 v[214:215], s[14:15], 0, v[174:175]
	global_load_lds_dwordx4 v[212:213], off
	v_lshl_add_u64 v[212:213], s[24:25], 0, v[172:173]
	s_add_i32 m0, s19, 0x2000
	s_nop 0
	global_load_lds_dwordx4 v[212:213], off
	v_lshl_add_u64 v[212:213], s[14:15], 0, v[180:181]
	s_mov_b32 m0, s33
	s_nop 0
	global_load_lds_dwordx4 v[212:213], off
	s_mov_b32 m0, s59
	s_nop 0
	global_load_lds_dwordx4 v[214:215], off
	s_waitcnt vmcnt(8)
	s_waitcnt lgkmcnt(0)
	s_barrier
	s_setprio 1
	s_waitcnt lgkmcnt(0)
	v_mfma_f32_16x16x32_bf16 v[78:81], v[130:133], v[162:165], v[78:81]
	v_mfma_f32_16x16x32_bf16 v[22:25], v[138:141], v[162:165], v[22:25]
	v_mfma_f32_16x16x32_bf16 v[70:73], v[130:133], v[176:179], v[70:73]
	v_mfma_f32_16x16x32_bf16 v[18:21], v[138:141], v[176:179], v[18:21]
	v_mfma_f32_16x16x32_bf16 v[66:69], v[130:133], v[190:193], v[66:69]
	v_mfma_f32_16x16x32_bf16 v[14:17], v[138:141], v[190:193], v[14:17]
	v_mfma_f32_16x16x32_bf16 v[86:89], v[130:133], v[198:201], v[86:89]
	v_mfma_f32_16x16x32_bf16 v[30:33], v[138:141], v[198:201], v[30:33]
	v_mfma_f32_16x16x32_bf16 v[78:81], v[134:137], v[166:169], v[78:81]
	v_mfma_f32_16x16x32_bf16 v[22:25], v[142:145], v[166:169], v[22:25]
	v_mfma_f32_16x16x32_bf16 v[70:73], v[134:137], v[186:189], v[70:73]
	v_mfma_f32_16x16x32_bf16 v[18:21], v[142:145], v[186:189], v[18:21]
	v_mfma_f32_16x16x32_bf16 v[66:69], v[134:137], v[194:197], v[66:69]
	v_mfma_f32_16x16x32_bf16 v[14:17], v[142:145], v[194:197], v[14:17]
	v_mfma_f32_16x16x32_bf16 v[86:89], v[134:137], v[202:205], v[86:89]
	v_mfma_f32_16x16x32_bf16 v[30:33], v[142:145], v[202:205], v[30:33]
	s_setprio 0
	s_setprio 1
	v_mfma_f32_16x16x32_bf16 v[74:77], v[146:149], v[162:165], v[74:77]
	v_mfma_f32_16x16x32_bf16 v[10:13], v[154:157], v[162:165], v[10:13]
	v_mfma_f32_16x16x32_bf16 v[62:65], v[146:149], v[176:179], v[62:65]
	v_mfma_f32_16x16x32_bf16 v[6:9], v[154:157], v[176:179], v[6:9]
	v_mfma_f32_16x16x32_bf16 v[58:61], v[146:149], v[190:193], v[58:61]
	v_mfma_f32_16x16x32_bf16 v[2:5], v[154:157], v[190:193], v[2:5]
	v_mfma_f32_16x16x32_bf16 v[82:85], v[146:149], v[198:201], v[82:85]
	v_mfma_f32_16x16x32_bf16 v[26:29], v[154:157], v[198:201], v[26:29]
	v_mfma_f32_16x16x32_bf16 v[74:77], v[150:153], v[166:169], v[74:77]
	v_mfma_f32_16x16x32_bf16 v[10:13], v[158:161], v[166:169], v[10:13]
	v_mfma_f32_16x16x32_bf16 v[62:65], v[150:153], v[186:189], v[62:65]
	v_mfma_f32_16x16x32_bf16 v[6:9], v[158:161], v[186:189], v[6:9]
	v_mfma_f32_16x16x32_bf16 v[58:61], v[150:153], v[194:197], v[58:61]
	v_mfma_f32_16x16x32_bf16 v[2:5], v[158:161], v[194:197], v[2:5]
	v_mfma_f32_16x16x32_bf16 v[82:85], v[150:153], v[202:205], v[82:85]
	v_mfma_f32_16x16x32_bf16 v[26:29], v[158:161], v[202:205], v[26:29]
	s_setprio 2
	s_barrier
	s_add_i32 s19, 0, 0x18000
	s_add_i32 s24, 0, 0x1c000
	v_add_u32_e32 v142, s19, v208
	v_add_u32_e32 v158, s24, v208
	ds_read_b128 v[130:133], v142
	ds_read_b128 v[134:137], v142 offset:1024
	ds_read_b128 v[138:141], v142 offset:2048
	ds_read_b128 v[142:145], v142 offset:3072
	ds_read_b128 v[146:149], v158
	ds_read_b128 v[150:153], v158 offset:1024
	ds_read_b128 v[154:157], v158 offset:2048
	ds_read_b128 v[158:161], v158 offset:3072
	s_add_u32 s14, s14, 0x80000
	s_addc_u32 s15, s15, 0
	s_mov_b32 m0, s76
	v_lshl_add_u64 v[216:217], s[14:15], 0, v[180:181]
	ds_read_b128 v[162:165], v209 offset:32768
	ds_read_b128 v[166:169], v209 offset:33792
	ds_read_b128 v[176:179], v209 offset:34816
	ds_read_b128 v[186:189], v209 offset:35840
	ds_read_b128 v[190:193], v209 offset:36864
	ds_read_b128 v[194:197], v209 offset:37888
	ds_read_b128 v[198:201], v209 offset:38912
	ds_read_b128 v[202:205], v209 offset:39936
	global_load_lds_dwordx4 v[216:217], off
	v_lshl_add_u64 v[216:217], s[14:15], 0, v[174:175]
	s_mov_b32 m0, s77
	s_nop 0
	global_load_lds_dwordx4 v[216:217], off
	s_waitcnt vmcnt(8)
	s_waitcnt lgkmcnt(0)
	s_barrier
	s_setprio 1
	s_waitcnt lgkmcnt(0)
	v_mfma_f32_16x16x32_bf16 v[122:125], v[130:133], v[162:165], v[122:125]
	v_mfma_f32_16x16x32_bf16 v[90:93], v[138:141], v[162:165], v[90:93]
	v_mfma_f32_16x16x32_bf16 v[110:113], v[130:133], v[176:179], v[110:113]
	v_mfma_f32_16x16x32_bf16 v[46:49], v[138:141], v[176:179], v[46:49]
	v_mfma_f32_16x16x32_bf16 v[106:109], v[130:133], v[190:193], v[106:109]
	v_mfma_f32_16x16x32_bf16 v[42:45], v[138:141], v[190:193], v[42:45]
	v_mfma_f32_16x16x32_bf16 v[126:129], v[130:133], v[198:201], v[126:129]
	v_mfma_f32_16x16x32_bf16 v[54:57], v[138:141], v[198:201], v[54:57]
	v_mfma_f32_16x16x32_bf16 v[122:125], v[134:137], v[166:169], v[122:125]
	v_mfma_f32_16x16x32_bf16 v[90:93], v[142:145], v[166:169], v[90:93]
	v_mfma_f32_16x16x32_bf16 v[110:113], v[134:137], v[186:189], v[110:113]
	v_mfma_f32_16x16x32_bf16 v[46:49], v[142:145], v[186:189], v[46:49]
	v_mfma_f32_16x16x32_bf16 v[106:109], v[134:137], v[194:197], v[106:109]
	v_mfma_f32_16x16x32_bf16 v[42:45], v[142:145], v[194:197], v[42:45]
	v_mfma_f32_16x16x32_bf16 v[126:129], v[134:137], v[202:205], v[126:129]
	v_mfma_f32_16x16x32_bf16 v[54:57], v[142:145], v[202:205], v[54:57]
	s_setprio 0
	s_setprio 1
	v_mfma_f32_16x16x32_bf16 v[114:117], v[146:149], v[162:165], v[114:117]
	v_mfma_f32_16x16x32_bf16 v[94:97], v[154:157], v[162:165], v[94:97]
	v_mfma_f32_16x16x32_bf16 v[102:105], v[146:149], v[176:179], v[102:105]
	v_mfma_f32_16x16x32_bf16 v[38:41], v[154:157], v[176:179], v[38:41]
	v_mfma_f32_16x16x32_bf16 v[98:101], v[146:149], v[190:193], v[98:101]
	v_mfma_f32_16x16x32_bf16 v[34:37], v[154:157], v[190:193], v[34:37]
	v_mfma_f32_16x16x32_bf16 v[118:121], v[146:149], v[198:201], v[118:121]
	v_mfma_f32_16x16x32_bf16 v[50:53], v[154:157], v[198:201], v[50:53]
	v_mfma_f32_16x16x32_bf16 v[114:117], v[150:153], v[166:169], v[114:117]
	v_mfma_f32_16x16x32_bf16 v[94:97], v[158:161], v[166:169], v[94:97]
	v_mfma_f32_16x16x32_bf16 v[102:105], v[150:153], v[186:189], v[102:105]
	v_mfma_f32_16x16x32_bf16 v[38:41], v[158:161], v[186:189], v[38:41]
	v_mfma_f32_16x16x32_bf16 v[98:101], v[150:153], v[194:197], v[98:101]
	v_mfma_f32_16x16x32_bf16 v[34:37], v[158:161], v[194:197], v[34:37]
	v_mfma_f32_16x16x32_bf16 v[118:121], v[150:153], v[202:205], v[118:121]
	v_mfma_f32_16x16x32_bf16 v[50:53], v[158:161], v[202:205], v[50:53]
	s_setprio 2
	s_barrier
	s_add_i32 s14, s19, s41
	v_lshl_add_u64 v[170:171], v[170:171], 0, s[94:95]
	s_mov_b32 m0, s14
	ds_read_b128 v[162:165], v209 offset:49152
	ds_read_b128 v[166:169], v209 offset:50176
	ds_read_b128 v[176:179], v209 offset:51200
	ds_read_b128 v[186:189], v209 offset:52224
	ds_read_b128 v[190:193], v209 offset:53248
	ds_read_b128 v[194:197], v209 offset:54272
	ds_read_b128 v[198:201], v209 offset:55296
	ds_read_b128 v[202:205], v209 offset:56320
	global_load_lds_dwordx4 v[170:171], off
	s_add_i32 m0, s14, 0x2000
	s_add_u32 s6, s6, 0x80080
	v_lshl_add_u64 v[170:171], v[210:211], 0, s[94:95]
	s_addc_u32 s7, s7, 0
	s_add_i32 s14, s24, s41
	global_load_lds_dwordx4 v[170:171], off
	v_lshl_add_u64 v[170:171], s[6:7], 0, v[0:1]
	s_mov_b32 m0, s14
	s_nop 0
	global_load_lds_dwordx4 v[170:171], off
	v_lshl_add_u64 v[170:171], s[6:7], 0, v[172:173]
	s_add_i32 m0, s14, 0x2000
	s_nop 0
	global_load_lds_dwordx4 v[170:171], off
	v_lshl_add_u64 v[170:171], v[212:213], 0, s[94:95]
	s_mov_b32 m0, s28
	s_nop 0
	global_load_lds_dwordx4 v[170:171], off
	v_lshl_add_u64 v[170:171], v[214:215], 0, s[94:95]
	s_mov_b32 m0, s82
	s_nop 0
	global_load_lds_dwordx4 v[170:171], off
	s_waitcnt vmcnt(8)
	s_waitcnt lgkmcnt(0)
	s_barrier
	s_setprio 1
	s_waitcnt lgkmcnt(0)
	v_mfma_f32_16x16x32_bf16 v[78:81], v[130:133], v[162:165], v[78:81]
	v_mfma_f32_16x16x32_bf16 v[22:25], v[138:141], v[162:165], v[22:25]
	v_mfma_f32_16x16x32_bf16 v[70:73], v[130:133], v[176:179], v[70:73]
	v_mfma_f32_16x16x32_bf16 v[18:21], v[138:141], v[176:179], v[18:21]
	v_mfma_f32_16x16x32_bf16 v[66:69], v[130:133], v[190:193], v[66:69]
	v_mfma_f32_16x16x32_bf16 v[14:17], v[138:141], v[190:193], v[14:17]
	v_mfma_f32_16x16x32_bf16 v[86:89], v[130:133], v[198:201], v[86:89]
	v_mfma_f32_16x16x32_bf16 v[30:33], v[138:141], v[198:201], v[30:33]
	v_mfma_f32_16x16x32_bf16 v[78:81], v[134:137], v[166:169], v[78:81]
	v_mfma_f32_16x16x32_bf16 v[22:25], v[142:145], v[166:169], v[22:25]
	v_mfma_f32_16x16x32_bf16 v[70:73], v[134:137], v[186:189], v[70:73]
	v_mfma_f32_16x16x32_bf16 v[18:21], v[142:145], v[186:189], v[18:21]
	v_mfma_f32_16x16x32_bf16 v[66:69], v[134:137], v[194:197], v[66:69]
	v_mfma_f32_16x16x32_bf16 v[14:17], v[142:145], v[194:197], v[14:17]
	v_mfma_f32_16x16x32_bf16 v[86:89], v[134:137], v[202:205], v[86:89]
	v_mfma_f32_16x16x32_bf16 v[30:33], v[142:145], v[202:205], v[30:33]
	s_setprio 0
	s_setprio 1
	v_mfma_f32_16x16x32_bf16 v[74:77], v[146:149], v[162:165], v[74:77]
	v_mfma_f32_16x16x32_bf16 v[10:13], v[154:157], v[162:165], v[10:13]
	v_mfma_f32_16x16x32_bf16 v[62:65], v[146:149], v[176:179], v[62:65]
	v_mfma_f32_16x16x32_bf16 v[6:9], v[154:157], v[176:179], v[6:9]
	v_mfma_f32_16x16x32_bf16 v[58:61], v[146:149], v[190:193], v[58:61]
	v_mfma_f32_16x16x32_bf16 v[2:5], v[154:157], v[190:193], v[2:5]
	v_mfma_f32_16x16x32_bf16 v[82:85], v[146:149], v[198:201], v[82:85]
	v_mfma_f32_16x16x32_bf16 v[26:29], v[154:157], v[198:201], v[26:29]
	v_mfma_f32_16x16x32_bf16 v[74:77], v[150:153], v[166:169], v[74:77]
	v_mfma_f32_16x16x32_bf16 v[10:13], v[158:161], v[166:169], v[10:13]
	v_mfma_f32_16x16x32_bf16 v[62:65], v[150:153], v[186:189], v[62:65]
	v_mfma_f32_16x16x32_bf16 v[6:9], v[158:161], v[186:189], v[6:9]
	v_mfma_f32_16x16x32_bf16 v[58:61], v[150:153], v[194:197], v[58:61]
	v_mfma_f32_16x16x32_bf16 v[2:5], v[158:161], v[194:197], v[2:5]
	v_mfma_f32_16x16x32_bf16 v[82:85], v[150:153], v[202:205], v[82:85]
	v_mfma_f32_16x16x32_bf16 v[26:29], v[158:161], v[202:205], v[26:29]
	s_setprio 2
	s_barrier
	s_add_i32 s18, s18, 2
	s_add_u32 s16, s16, 0x100
	s_addc_u32 s17, s17, 0
	s_add_u32 s12, s12, 0x100
	s_addc_u32 s13, s13, 0
	s_cmp_gt_u32 s18, 29
	s_cbranch_scc0 .LBB0_773
	s_and_b64 vcc, exec, s[72:73]
	s_cbranch_vccz .LBB0_776
	s_barrier

.LBB0_924:
	s_add_u32 s10, s12, 0x100
	s_addc_u32 s11, s13, 0
	s_add_i32 s67, 0, 0x10000
	s_cmpk_eq_i32 s66, 0x54
	s_cselect_b32 s45, s39, s11
	s_cselect_b32 s44, s38, s10
	s_cselect_b32 s15, s43, s65
	s_cselect_b32 s14, s42, s64
	s_add_i32 s68, 0, 0x14000
	v_add_u32_e32 v142, s67, v190
	v_add_u32_e32 v168, s68, v190
	ds_read_b128 v[122:125], v142
	ds_read_b128 v[126:129], v142 offset:1024
	ds_read_b128 v[138:141], v142 offset:2048
	ds_read_b128 v[142:145], v142 offset:3072
	ds_read_b128 v[146:149], v168
	ds_read_b128 v[150:153], v168 offset:1024
	ds_read_b128 v[154:157], v168 offset:2048
	ds_read_b128 v[168:171], v168 offset:3072
	v_lshl_add_u64 v[208:209], s[12:13], 0, v[166:167]
	s_add_i32 m0, s40, 0xc000
	ds_read_b128 v[172:175], v191
	ds_read_b128 v[176:179], v191 offset:1024
	ds_read_b128 v[180:183], v191 offset:2048
	ds_read_b128 v[184:187], v191 offset:3072
	ds_read_b128 v[192:195], v191 offset:4096
	ds_read_b128 v[196:199], v191 offset:5120
	ds_read_b128 v[200:203], v191 offset:6144
	ds_read_b128 v[204:207], v191 offset:7168
	global_load_lds_dwordx4 v[208:209], off
	v_lshl_add_u64 v[208:209], s[12:13], 0, v[164:165]
	s_add_i32 m0, s40, 0xe000
	s_nop 0
	global_load_lds_dwordx4 v[208:209], off
	s_waitcnt vmcnt(8)
	s_waitcnt lgkmcnt(0)
	s_barrier
	s_setprio 1
	s_waitcnt lgkmcnt(0)
	v_mfma_f32_16x16x32_bf16 v[134:137], v[122:125], v[172:175], v[134:137]
	v_mfma_f32_16x16x32_bf16 v[130:133], v[138:141], v[172:175], v[130:133]
	v_mfma_f32_16x16x32_bf16 v[110:113], v[122:125], v[180:183], v[110:113]
	v_mfma_f32_16x16x32_bf16 v[106:109], v[138:141], v[180:183], v[106:109]
	v_mfma_f32_16x16x32_bf16 v[94:97], v[122:125], v[192:195], v[94:97]
	v_mfma_f32_16x16x32_bf16 v[90:93], v[138:141], v[192:195], v[90:93]
	v_mfma_f32_16x16x32_bf16 v[78:81], v[122:125], v[200:203], v[78:81]
	v_mfma_f32_16x16x32_bf16 v[74:77], v[138:141], v[200:203], v[74:77]
	v_mfma_f32_16x16x32_bf16 v[134:137], v[126:129], v[176:179], v[134:137]
	v_mfma_f32_16x16x32_bf16 v[130:133], v[142:145], v[176:179], v[130:133]
	v_mfma_f32_16x16x32_bf16 v[110:113], v[126:129], v[184:187], v[110:113]
	v_mfma_f32_16x16x32_bf16 v[106:109], v[142:145], v[184:187], v[106:109]
	v_mfma_f32_16x16x32_bf16 v[94:97], v[126:129], v[196:199], v[94:97]
	v_mfma_f32_16x16x32_bf16 v[90:93], v[142:145], v[196:199], v[90:93]
	v_mfma_f32_16x16x32_bf16 v[78:81], v[126:129], v[204:207], v[78:81]
	v_mfma_f32_16x16x32_bf16 v[74:77], v[142:145], v[204:207], v[74:77]
	s_setprio 0
	s_setprio 1
	v_mfma_f32_16x16x32_bf16 v[118:121], v[146:149], v[172:175], v[118:121]
	v_mfma_f32_16x16x32_bf16 v[114:117], v[154:157], v[172:175], v[114:117]
	v_mfma_f32_16x16x32_bf16 v[102:105], v[146:149], v[180:183], v[102:105]
	v_mfma_f32_16x16x32_bf16 v[98:101], v[154:157], v[180:183], v[98:101]
	v_mfma_f32_16x16x32_bf16 v[86:89], v[146:149], v[192:195], v[86:89]
	v_mfma_f32_16x16x32_bf16 v[82:85], v[154:157], v[192:195], v[82:85]
	v_mfma_f32_16x16x32_bf16 v[70:73], v[146:149], v[200:203], v[70:73]
	v_mfma_f32_16x16x32_bf16 v[66:69], v[154:157], v[200:203], v[66:69]
	v_mfma_f32_16x16x32_bf16 v[118:121], v[150:153], v[176:179], v[118:121]
	v_mfma_f32_16x16x32_bf16 v[114:117], v[168:171], v[176:179], v[114:117]
	v_mfma_f32_16x16x32_bf16 v[102:105], v[150:153], v[184:187], v[102:105]
	v_mfma_f32_16x16x32_bf16 v[98:101], v[168:171], v[184:187], v[98:101]
	v_mfma_f32_16x16x32_bf16 v[86:89], v[150:153], v[196:199], v[86:89]
	v_mfma_f32_16x16x32_bf16 v[82:85], v[168:171], v[196:199], v[82:85]
	v_mfma_f32_16x16x32_bf16 v[70:73], v[150:153], v[204:207], v[70:73]
	v_mfma_f32_16x16x32_bf16 v[66:69], v[168:171], v[204:207], v[66:69]
	s_setprio 2
	s_barrier
	s_add_i32 s12, s67, s37
	v_lshl_add_u64 v[208:209], s[14:15], 0, v[0:1]
	s_mov_b32 m0, s12
	ds_read_b128 v[172:175], v191 offset:16384
	ds_read_b128 v[176:179], v191 offset:17408
	ds_read_b128 v[180:183], v191 offset:18432
	ds_read_b128 v[184:187], v191 offset:19456
	ds_read_b128 v[192:195], v191 offset:20480
	ds_read_b128 v[196:199], v191 offset:21504
	ds_read_b128 v[200:203], v191 offset:22528
	ds_read_b128 v[204:207], v191 offset:23552
	global_load_lds_dwordx4 v[208:209], off
	s_add_i32 m0, s12, 0x2000
	s_add_u32 s12, s14, 0x160000
	v_lshl_add_u64 v[210:211], s[14:15], 0, v[158:159]
	s_addc_u32 s13, s15, 0
	s_add_i32 s67, s68, s37
	global_load_lds_dwordx4 v[210:211], off
	v_lshl_add_u64 v[212:213], s[12:13], 0, v[0:1]
	s_mov_b32 m0, s67
	v_lshl_add_u64 v[214:215], s[44:45], 0, v[160:161]
	global_load_lds_dwordx4 v[212:213], off
	v_lshl_add_u64 v[212:213], s[12:13], 0, v[158:159]
	s_add_i32 m0, s67, 0x2000
	s_nop 0
	global_load_lds_dwordx4 v[212:213], off
	v_lshl_add_u64 v[212:213], s[44:45], 0, v[162:163]
	s_mov_b32 m0, s40
	s_nop 0
	global_load_lds_dwordx4 v[212:213], off
	s_mov_b32 m0, s41
	s_nop 0
	global_load_lds_dwordx4 v[214:215], off
	s_waitcnt vmcnt(8)
	s_waitcnt lgkmcnt(0)
	s_barrier
	s_setprio 1
	s_waitcnt lgkmcnt(0)
	v_mfma_f32_16x16x32_bf16 v[62:65], v[122:125], v[172:175], v[62:65]
	v_mfma_f32_16x16x32_bf16 v[58:61], v[138:141], v[172:175], v[58:61]
	v_mfma_f32_16x16x32_bf16 v[46:49], v[122:125], v[180:183], v[46:49]
	v_mfma_f32_16x16x32_bf16 v[42:45], v[138:141], v[180:183], v[42:45]
	v_mfma_f32_16x16x32_bf16 v[30:33], v[122:125], v[192:195], v[30:33]
	v_mfma_f32_16x16x32_bf16 v[26:29], v[138:141], v[192:195], v[26:29]
	v_mfma_f32_16x16x32_bf16 v[14:17], v[122:125], v[200:203], v[14:17]
	v_mfma_f32_16x16x32_bf16 v[10:13], v[138:141], v[200:203], v[10:13]
	v_mfma_f32_16x16x32_bf16 v[62:65], v[126:129], v[176:179], v[62:65]
	v_mfma_f32_16x16x32_bf16 v[58:61], v[142:145], v[176:179], v[58:61]
	v_mfma_f32_16x16x32_bf16 v[46:49], v[126:129], v[184:187], v[46:49]
	v_mfma_f32_16x16x32_bf16 v[42:45], v[142:145], v[184:187], v[42:45]
	v_mfma_f32_16x16x32_bf16 v[30:33], v[126:129], v[196:199], v[30:33]
	v_mfma_f32_16x16x32_bf16 v[26:29], v[142:145], v[196:199], v[26:29]
	v_mfma_f32_16x16x32_bf16 v[14:17], v[126:129], v[204:207], v[14:17]
	v_mfma_f32_16x16x32_bf16 v[10:13], v[142:145], v[204:207], v[10:13]
	s_setprio 0
	s_setprio 1
	v_mfma_f32_16x16x32_bf16 v[54:57], v[146:149], v[172:175], v[54:57]
	v_mfma_f32_16x16x32_bf16 v[50:53], v[154:157], v[172:175], v[50:53]
	v_mfma_f32_16x16x32_bf16 v[38:41], v[146:149], v[180:183], v[38:41]
	v_mfma_f32_16x16x32_bf16 v[34:37], v[154:157], v[180:183], v[34:37]
	v_mfma_f32_16x16x32_bf16 v[22:25], v[146:149], v[192:195], v[22:25]
	v_mfma_f32_16x16x32_bf16 v[18:21], v[154:157], v[192:195], v[18:21]
	v_mfma_f32_16x16x32_bf16 v[6:9], v[146:149], v[200:203], v[6:9]
	v_mfma_f32_16x16x32_bf16 v[2:5], v[154:157], v[200:203], v[2:5]
	v_mfma_f32_16x16x32_bf16 v[54:57], v[150:153], v[176:179], v[54:57]
	v_mfma_f32_16x16x32_bf16 v[50:53], v[168:171], v[176:179], v[50:53]
	v_mfma_f32_16x16x32_bf16 v[38:41], v[150:153], v[184:187], v[38:41]
	v_mfma_f32_16x16x32_bf16 v[34:37], v[168:171], v[184:187], v[34:37]
	v_mfma_f32_16x16x32_bf16 v[22:25], v[150:153], v[196:199], v[22:25]
	v_mfma_f32_16x16x32_bf16 v[18:21], v[168:171], v[196:199], v[18:21]
	v_mfma_f32_16x16x32_bf16 v[6:9], v[150:153], v[204:207], v[6:9]
	v_mfma_f32_16x16x32_bf16 v[2:5], v[168:171], v[204:207], v[2:5]
	s_setprio 2
	s_barrier
	s_add_i32 s67, 0, 0x18000
	s_add_i32 s68, 0, 0x1c000
	v_add_u32_e32 v142, s67, v190
	v_add_u32_e32 v168, s68, v190
	ds_read_b128 v[122:125], v142
	ds_read_b128 v[126:129], v142 offset:1024
	ds_read_b128 v[138:141], v142 offset:2048
	ds_read_b128 v[142:145], v142 offset:3072
	ds_read_b128 v[146:149], v168
	ds_read_b128 v[150:153], v168 offset:1024
	ds_read_b128 v[154:157], v168 offset:2048
	ds_read_b128 v[168:171], v168 offset:3072
	s_add_u32 s12, s44, 0x160000
	s_addc_u32 s13, s45, 0
	s_mov_b32 m0, s48
	v_lshl_add_u64 v[216:217], s[12:13], 0, v[162:163]
	ds_read_b128 v[172:175], v191 offset:32768
	ds_read_b128 v[176:179], v191 offset:33792
	ds_read_b128 v[180:183], v191 offset:34816
	ds_read_b128 v[184:187], v191 offset:35840
	ds_read_b128 v[192:195], v191 offset:36864
	ds_read_b128 v[196:199], v191 offset:37888
	ds_read_b128 v[200:203], v191 offset:38912
	ds_read_b128 v[204:207], v191 offset:39936
	global_load_lds_dwordx4 v[216:217], off
	v_lshl_add_u64 v[216:217], s[12:13], 0, v[160:161]
	s_mov_b32 m0, s52
	s_nop 0
	global_load_lds_dwordx4 v[216:217], off
	s_waitcnt vmcnt(8)
	s_waitcnt lgkmcnt(0)
	s_barrier
	s_setprio 1
	s_waitcnt lgkmcnt(0)
	v_mfma_f32_16x16x32_bf16 v[134:137], v[122:125], v[172:175], v[134:137]
	v_mfma_f32_16x16x32_bf16 v[130:133], v[138:141], v[172:175], v[130:133]
	v_mfma_f32_16x16x32_bf16 v[110:113], v[122:125], v[180:183], v[110:113]
	v_mfma_f32_16x16x32_bf16 v[106:109], v[138:141], v[180:183], v[106:109]
	v_mfma_f32_16x16x32_bf16 v[94:97], v[122:125], v[192:195], v[94:97]
	v_mfma_f32_16x16x32_bf16 v[90:93], v[138:141], v[192:195], v[90:93]
	v_mfma_f32_16x16x32_bf16 v[78:81], v[122:125], v[200:203], v[78:81]
	v_mfma_f32_16x16x32_bf16 v[74:77], v[138:141], v[200:203], v[74:77]
	v_mfma_f32_16x16x32_bf16 v[134:137], v[126:129], v[176:179], v[134:137]
	v_mfma_f32_16x16x32_bf16 v[130:133], v[142:145], v[176:179], v[130:133]
	v_mfma_f32_16x16x32_bf16 v[110:113], v[126:129], v[184:187], v[110:113]
	v_mfma_f32_16x16x32_bf16 v[106:109], v[142:145], v[184:187], v[106:109]
	v_mfma_f32_16x16x32_bf16 v[94:97], v[126:129], v[196:199], v[94:97]
	v_mfma_f32_16x16x32_bf16 v[90:93], v[142:145], v[196:199], v[90:93]
	v_mfma_f32_16x16x32_bf16 v[78:81], v[126:129], v[204:207], v[78:81]
	v_mfma_f32_16x16x32_bf16 v[74:77], v[142:145], v[204:207], v[74:77]
	s_setprio 0
	s_setprio 1
	v_mfma_f32_16x16x32_bf16 v[118:121], v[146:149], v[172:175], v[118:121]
	v_mfma_f32_16x16x32_bf16 v[114:117], v[154:157], v[172:175], v[114:117]
	v_mfma_f32_16x16x32_bf16 v[102:105], v[146:149], v[180:183], v[102:105]
	v_mfma_f32_16x16x32_bf16 v[98:101], v[154:157], v[180:183], v[98:101]
	v_mfma_f32_16x16x32_bf16 v[86:89], v[146:149], v[192:195], v[86:89]
	v_mfma_f32_16x16x32_bf16 v[82:85], v[154:157], v[192:195], v[82:85]
	v_mfma_f32_16x16x32_bf16 v[70:73], v[146:149], v[200:203], v[70:73]
	v_mfma_f32_16x16x32_bf16 v[66:69], v[154:157], v[200:203], v[66:69]
	v_mfma_f32_16x16x32_bf16 v[118:121], v[150:153], v[176:179], v[118:121]
	v_mfma_f32_16x16x32_bf16 v[114:117], v[168:171], v[176:179], v[114:117]
	v_mfma_f32_16x16x32_bf16 v[102:105], v[150:153], v[184:187], v[102:105]
	v_mfma_f32_16x16x32_bf16 v[98:101], v[168:171], v[184:187], v[98:101]
	v_mfma_f32_16x16x32_bf16 v[86:89], v[150:153], v[196:199], v[86:89]
	v_mfma_f32_16x16x32_bf16 v[82:85], v[168:171], v[196:199], v[82:85]
	v_mfma_f32_16x16x32_bf16 v[70:73], v[150:153], v[204:207], v[70:73]
	v_mfma_f32_16x16x32_bf16 v[66:69], v[168:171], v[204:207], v[66:69]
	s_setprio 2
	s_barrier
	s_add_i32 s12, s67, s37
	v_lshl_add_u64 v[208:209], v[208:209], 0, s[94:95]
	s_mov_b32 m0, s12
	ds_read_b128 v[172:175], v191 offset:49152
	ds_read_b128 v[176:179], v191 offset:50176
	ds_read_b128 v[180:183], v191 offset:51200
	ds_read_b128 v[184:187], v191 offset:52224
	ds_read_b128 v[192:195], v191 offset:53248
	ds_read_b128 v[196:199], v191 offset:54272
	ds_read_b128 v[200:203], v191 offset:55296
	ds_read_b128 v[204:207], v191 offset:56320
	global_load_lds_dwordx4 v[208:209], off
	s_add_i32 m0, s12, 0x2000
	s_add_u32 s12, s14, 0x160080
	v_lshl_add_u64 v[208:209], v[210:211], 0, s[94:95]
	s_addc_u32 s13, s15, 0
	s_add_i32 s14, s68, s37
	global_load_lds_dwordx4 v[208:209], off
	v_lshl_add_u64 v[208:209], s[12:13], 0, v[0:1]
	s_mov_b32 m0, s14
	s_nop 0
	global_load_lds_dwordx4 v[208:209], off
	v_lshl_add_u64 v[208:209], s[12:13], 0, v[158:159]
	s_add_i32 m0, s14, 0x2000
	s_nop 0
	global_load_lds_dwordx4 v[208:209], off
	v_lshl_add_u64 v[208:209], v[212:213], 0, s[94:95]
	s_mov_b32 m0, s58
	s_nop 0
	global_load_lds_dwordx4 v[208:209], off
	v_lshl_add_u64 v[208:209], v[214:215], 0, s[94:95]
	s_mov_b32 m0, s59
	s_nop 0
	global_load_lds_dwordx4 v[208:209], off
	s_waitcnt vmcnt(8)
	s_waitcnt lgkmcnt(0)
	s_barrier
	s_setprio 1
	s_waitcnt lgkmcnt(0)
	v_mfma_f32_16x16x32_bf16 v[62:65], v[122:125], v[172:175], v[62:65]
	v_mfma_f32_16x16x32_bf16 v[58:61], v[138:141], v[172:175], v[58:61]
	v_mfma_f32_16x16x32_bf16 v[46:49], v[122:125], v[180:183], v[46:49]
	v_mfma_f32_16x16x32_bf16 v[42:45], v[138:141], v[180:183], v[42:45]
	v_mfma_f32_16x16x32_bf16 v[30:33], v[122:125], v[192:195], v[30:33]
	v_mfma_f32_16x16x32_bf16 v[26:29], v[138:141], v[192:195], v[26:29]
	v_mfma_f32_16x16x32_bf16 v[14:17], v[122:125], v[200:203], v[14:17]
	v_mfma_f32_16x16x32_bf16 v[10:13], v[138:141], v[200:203], v[10:13]
	v_mfma_f32_16x16x32_bf16 v[62:65], v[126:129], v[176:179], v[62:65]
	v_mfma_f32_16x16x32_bf16 v[58:61], v[142:145], v[176:179], v[58:61]
	v_mfma_f32_16x16x32_bf16 v[46:49], v[126:129], v[184:187], v[46:49]
	v_mfma_f32_16x16x32_bf16 v[42:45], v[142:145], v[184:187], v[42:45]
	v_mfma_f32_16x16x32_bf16 v[30:33], v[126:129], v[196:199], v[30:33]
	v_mfma_f32_16x16x32_bf16 v[26:29], v[142:145], v[196:199], v[26:29]
	v_mfma_f32_16x16x32_bf16 v[14:17], v[126:129], v[204:207], v[14:17]
	v_mfma_f32_16x16x32_bf16 v[10:13], v[142:145], v[204:207], v[10:13]
	s_setprio 0
	s_setprio 1
	v_mfma_f32_16x16x32_bf16 v[54:57], v[146:149], v[172:175], v[54:57]
	v_mfma_f32_16x16x32_bf16 v[50:53], v[154:157], v[172:175], v[50:53]
	v_mfma_f32_16x16x32_bf16 v[38:41], v[146:149], v[180:183], v[38:41]
	v_mfma_f32_16x16x32_bf16 v[34:37], v[154:157], v[180:183], v[34:37]
	v_mfma_f32_16x16x32_bf16 v[22:25], v[146:149], v[192:195], v[22:25]
	v_mfma_f32_16x16x32_bf16 v[18:21], v[154:157], v[192:195], v[18:21]
	v_mfma_f32_16x16x32_bf16 v[6:9], v[146:149], v[200:203], v[6:9]
	v_mfma_f32_16x16x32_bf16 v[2:5], v[154:157], v[200:203], v[2:5]
	v_mfma_f32_16x16x32_bf16 v[54:57], v[150:153], v[176:179], v[54:57]
	v_mfma_f32_16x16x32_bf16 v[50:53], v[168:171], v[176:179], v[50:53]
	v_mfma_f32_16x16x32_bf16 v[38:41], v[150:153], v[184:187], v[38:41]
	v_mfma_f32_16x16x32_bf16 v[34:37], v[168:171], v[184:187], v[34:37]
	v_mfma_f32_16x16x32_bf16 v[22:25], v[150:153], v[196:199], v[22:25]
	v_mfma_f32_16x16x32_bf16 v[18:21], v[168:171], v[196:199], v[18:21]
	v_mfma_f32_16x16x32_bf16 v[6:9], v[150:153], v[204:207], v[6:9]
	v_mfma_f32_16x16x32_bf16 v[2:5], v[168:171], v[204:207], v[2:5]
	s_setprio 2
	s_barrier
	s_add_i32 s66, s66, 2
	s_add_u32 s64, s64, 0x100
	s_addc_u32 s65, s65, 0
	s_cmpk_gt_u32 s66, 0x55
	s_mov_b64 s[12:13], s[10:11]
	s_cbranch_scc0 .LBB0_924
	s_and_b64 vcc, exec, s[24:25]
	s_cbranch_vccz .LBB0_927
	s_barrier
